# v009 + attention QK^T: K-fragment LDS reads issued one key tile earlier (two fragment buffers, v240-255 added), score chains accumulate in place
# baseline (speedup 1.0000x reference)
; #define LAS __attribute__((address_space(3)))
; __device__ __forceinline__ void segment(LAS unsigned char* lds, const bf16* __restrict__ QKV, bf16* __restrict__ Og, float* __restrict__ L2, int bl, int g, int h, int r, int dil, int n0, int cnt, int tid) {
;     ...
;         { bf16x8 kf[2][4];
;             { const int slot0 = (w >> 3) ? cur : prv; const LAS unsigned char* kb0 = lds + slot0 * SLOTB + (w & 7) * 4096;
; #pragma unroll
;               for (int s = 0; s < 4; ++s) kf[0][s] = *(const LAS bf16x8*)(kb0 + koff[s]); }
; #pragma unroll
;             for (int kt = 0; kt < 9; ++kt) {
;                 if (kt < 8) { const int tt = w + kt + 1; const int slot = (tt >> 3) ? cur : prv; const LAS unsigned char* kb = lds + slot * SLOTB + (tt & 7) * 4096;
; #pragma unroll
;                     for (int s = 0; s < 4; ++s) kf[(kt + 1) & 1][s] = *(const LAS bf16x8*)(kb + koff[s]); }
;                 f32x4 a = {0.f, 0.f, 0.f, 0.f};
; #pragma unroll
;                 for (int s = 0; s < 4; ++s) a = __builtin_amdgcn_mfma_f32_16x16x32_bf16(kf[kt & 1][s], qf[s], a, 0, 0, 0);
;                 sc[kt] = a;
;                 __builtin_amdgcn_sched_barrier(0); } }
.LBB0_298:
	s_xor_b32 s71, s51, 1
	s_and_b64 s[52:53], s[42:43], exec
	s_cselect_b32 s36, s71, s51
	s_lshl_b32 s74, s36, 15
	s_add_i32 s36, s24, s74
	v_add_u32_e32 v0, s36, v123
	v_add_u32_e32 v1, s36, v124
	ds_read_b128 v[216:219], v0
	ds_read_b128 v[220:223], v1
	v_add_u32_e32 v0, s36, v125
	v_add_u32_e32 v1, s36, v126
	ds_read_b128 v[224:227], v0
	ds_read_b128 v[228:231], v1
	s_and_b64 s[52:53], s[84:85], exec
	s_cselect_b32 s36, s71, s51
	s_lshl_b32 s75, s36, 15
	s_add_i32 s36, s26, s75
	v_add_u32_e32 v0, s36, v123
	v_add_u32_e32 v1, s36, v124
	ds_read_b128 v[240:243], v0
	ds_read_b128 v[244:247], v1
	v_add_u32_e32 v0, s36, v125
	v_add_u32_e32 v1, s36, v126
	ds_read_b128 v[248:251], v0
	ds_read_b128 v[252:255], v1
	s_waitcnt lgkmcnt(7)
	v_mfma_f32_16x16x32_bf16 v[184:187], v[216:219], v[52:55], 0
	s_waitcnt lgkmcnt(6)
	v_mfma_f32_16x16x32_bf16 v[184:187], v[220:223], v[56:59], v[184:187]
	s_waitcnt lgkmcnt(5)
	v_mfma_f32_16x16x32_bf16 v[184:187], v[224:227], v[60:63], v[184:187]
	s_waitcnt lgkmcnt(4)
	v_mfma_f32_16x16x32_bf16 v[184:187], v[228:231], v[64:67], v[184:187]
	s_and_b64 s[52:53], s[86:87], exec
	s_cselect_b32 s36, s71, s51
	s_lshl_b32 s36, s36, 15
	s_add_i32 s50, s27, s36
	v_add_u32_e32 v0, s50, v123
	v_add_u32_e32 v1, s50, v124
	ds_read_b128 v[216:219], v0
	ds_read_b128 v[220:223], v1
	v_add_u32_e32 v0, s50, v125
	v_add_u32_e32 v1, s50, v126
	ds_read_b128 v[224:227], v0
	ds_read_b128 v[228:231], v1
	s_waitcnt lgkmcnt(7)
	v_mfma_f32_16x16x32_bf16 v[188:191], v[240:243], v[52:55], 0
	s_waitcnt lgkmcnt(6)
	v_mfma_f32_16x16x32_bf16 v[188:191], v[244:247], v[56:59], v[188:191]
	s_waitcnt lgkmcnt(5)
	v_mfma_f32_16x16x32_bf16 v[188:191], v[248:251], v[60:63], v[188:191]
	s_waitcnt lgkmcnt(4)
	v_mfma_f32_16x16x32_bf16 v[188:191], v[252:255], v[64:67], v[188:191]
	s_and_b64 s[52:53], s[88:89], exec
	s_cselect_b32 s50, s71, s51
	s_lshl_b32 s67, s50, 15
	s_add_i32 s50, s28, s67
	v_add_u32_e32 v0, s50, v123
	v_add_u32_e32 v1, s50, v124
	ds_read_b128 v[240:243], v0
	ds_read_b128 v[244:247], v1
	v_add_u32_e32 v0, s50, v125
	v_add_u32_e32 v1, s50, v126
	ds_read_b128 v[248:251], v0
	ds_read_b128 v[252:255], v1
	s_waitcnt lgkmcnt(7)
	v_mfma_f32_16x16x32_bf16 v[192:195], v[216:219], v[52:55], 0
	s_waitcnt lgkmcnt(6)
	v_mfma_f32_16x16x32_bf16 v[192:195], v[220:223], v[56:59], v[192:195]
	s_waitcnt lgkmcnt(5)
	v_mfma_f32_16x16x32_bf16 v[192:195], v[224:227], v[60:63], v[192:195]
	s_waitcnt lgkmcnt(4)
	v_mfma_f32_16x16x32_bf16 v[192:195], v[228:231], v[64:67], v[192:195]
	s_and_b64 s[52:53], s[90:91], exec
	s_cselect_b32 s50, s71, s51
	s_lshl_b32 s52, s50, 15
	s_add_i32 s50, s29, s52
	v_add_u32_e32 v0, s50, v123
	v_add_u32_e32 v1, s50, v124
	ds_read_b128 v[216:219], v0
	ds_read_b128 v[220:223], v1
	v_add_u32_e32 v0, s50, v125
	v_add_u32_e32 v1, s50, v126
	ds_read_b128 v[224:227], v0
	ds_read_b128 v[228:231], v1
	s_waitcnt lgkmcnt(7)
	v_mfma_f32_16x16x32_bf16 v[196:199], v[240:243], v[52:55], 0
	s_waitcnt lgkmcnt(6)
	v_mfma_f32_16x16x32_bf16 v[196:199], v[244:247], v[56:59], v[196:199]
	s_waitcnt lgkmcnt(5)
	v_mfma_f32_16x16x32_bf16 v[196:199], v[248:251], v[60:63], v[196:199]
	s_waitcnt lgkmcnt(4)
	v_mfma_f32_16x16x32_bf16 v[196:199], v[252:255], v[64:67], v[196:199]
	s_and_b64 vcc, s[92:93], exec
	s_cselect_b32 s50, s71, s51
	s_lshl_b32 s53, s50, 15
	s_add_i32 s50, s30, s53
	v_add_u32_e32 v0, s50, v123
	v_add_u32_e32 v1, s50, v124
	ds_read_b128 v[240:243], v0
	ds_read_b128 v[244:247], v1
	v_add_u32_e32 v0, s50, v125
	v_add_u32_e32 v1, s50, v126
	ds_read_b128 v[248:251], v0
	ds_read_b128 v[252:255], v1
	s_waitcnt lgkmcnt(7)
	v_mfma_f32_16x16x32_bf16 v[200:203], v[216:219], v[52:55], 0
	s_waitcnt lgkmcnt(6)
	v_mfma_f32_16x16x32_bf16 v[200:203], v[220:223], v[56:59], v[200:203]
	s_waitcnt lgkmcnt(5)
	v_mfma_f32_16x16x32_bf16 v[200:203], v[224:227], v[60:63], v[200:203]
	s_waitcnt lgkmcnt(4)
	v_mfma_f32_16x16x32_bf16 v[200:203], v[228:231], v[64:67], v[200:203]
	s_and_b64 vcc, s[94:95], exec
	s_cselect_b32 s50, s71, s51
	s_lshl_b32 s50, s50, 15
	s_add_i32 s72, s31, s50
	v_add_u32_e32 v0, s72, v123
	v_add_u32_e32 v1, s72, v124
	ds_read_b128 v[216:219], v0
	ds_read_b128 v[220:223], v1
	v_add_u32_e32 v0, s72, v125
	v_add_u32_e32 v1, s72, v126
	ds_read_b128 v[224:227], v0
	ds_read_b128 v[228:231], v1
	s_waitcnt lgkmcnt(7)
	v_mfma_f32_16x16x32_bf16 v[204:207], v[240:243], v[52:55], 0
	s_waitcnt lgkmcnt(6)
	v_mfma_f32_16x16x32_bf16 v[204:207], v[244:247], v[56:59], v[204:207]
	s_waitcnt lgkmcnt(5)
	v_mfma_f32_16x16x32_bf16 v[204:207], v[248:251], v[60:63], v[204:207]
	s_waitcnt lgkmcnt(4)
	v_mfma_f32_16x16x32_bf16 v[204:207], v[252:255], v[64:67], v[204:207]
	s_and_b64 vcc, s[96:97], exec
	s_cselect_b32 s51, s71, s51
	s_lshl_b32 s51, s51, 15
	s_add_i32 s71, s38, s51
	v_add_u32_e32 v0, s71, v123
	v_add_u32_e32 v1, s71, v124
	ds_read_b128 v[240:243], v0
	ds_read_b128 v[244:247], v1
	v_add_u32_e32 v0, s71, v125
	v_add_u32_e32 v1, s71, v126
	ds_read_b128 v[248:251], v0
	ds_read_b128 v[252:255], v1
	s_waitcnt lgkmcnt(7)
	v_mfma_f32_16x16x32_bf16 v[208:211], v[216:219], v[52:55], 0
	s_waitcnt lgkmcnt(6)
	v_mfma_f32_16x16x32_bf16 v[208:211], v[220:223], v[56:59], v[208:211]
	s_waitcnt lgkmcnt(5)
	v_mfma_f32_16x16x32_bf16 v[208:211], v[224:227], v[60:63], v[208:211]
	s_waitcnt lgkmcnt(4)
	v_mfma_f32_16x16x32_bf16 v[208:211], v[228:231], v[64:67], v[208:211]
	s_add_i32 s39, s39, s40
	v_add_u32_e32 v0, s39, v123
	v_add_u32_e32 v1, s39, v124
	ds_read_b128 v[216:219], v0
	ds_read_b128 v[220:223], v1
	v_add_u32_e32 v0, s39, v125
	v_add_u32_e32 v1, s39, v126
	ds_read_b128 v[224:227], v0
	ds_read_b128 v[228:231], v1
	s_waitcnt lgkmcnt(7)
; #define LAS __attribute__((address_space(3)))
; __device__ __forceinline__ void segment(LAS unsigned char* lds, const bf16* __restrict__ QKV, bf16* __restrict__ Og, float* __restrict__ L2, int bl, int g, int h, int r, int dil, int n0, int cnt, int tid) {
;     ...
;             for (int kt = 0; kt < 9; ++kt) {
;                 if (kt < 8) { const int tt = w + kt + 1; const int slot = (tt >> 3) ? cur : prv; const LAS unsigned char* kb = lds + slot * SLOTB + (tt & 7) * 4096;
; #pragma unroll
;                     for (int s = 0; s < 4; ++s) kf[(kt + 1) & 1][s] = *(const LAS bf16x8*)(kb + koff[s]); }
;                 f32x4 a = {0.f, 0.f, 0.f, 0.f};
; #pragma unroll
;                 for (int s = 0; s < 4; ++s) a = __builtin_amdgcn_mfma_f32_16x16x32_bf16(kf[kt & 1][s], qf[s], a, 0, 0, 0);
;                 sc[kt] = a;
;                 __builtin_amdgcn_sched_barrier(0); } }
;         const bool firstblk = (n == 0);
;         float mx = -INFINITY;
; #pragma unroll
;         for (int kt = 0; kt < 9; ++kt)
; #pragma unroll
;             for (int i = 0; i < 4; ++i) { float v = sc[kt][i] + (basel + cb * (float)(16 * kt + i)); bool valid = true;
;                 if (kt == 0) valid = (4 * gq + i >= lq);
;                 if (kt == 8) valid = (4 * gq + i <= lq);
;                 if (firstblk && (w + kt) < 8) valid = false;
;                 v = valid ? v : -INFINITY; sc[kt][i] = v; mx = fmaxf(mx, v); }
;         mx = fmaxf(mx, __shfl_xor(mx, 16)); mx = fmaxf(mx, __shfl_xor(mx, 32));
	v_mfma_f32_16x16x32_bf16 v[212:215], v[240:243], v[52:55], 0
	s_waitcnt lgkmcnt(6)
	v_mfma_f32_16x16x32_bf16 v[212:215], v[244:247], v[56:59], v[212:215]
	s_waitcnt lgkmcnt(5)
	v_mfma_f32_16x16x32_bf16 v[212:215], v[248:251], v[60:63], v[212:215]
	s_waitcnt lgkmcnt(4)
	v_mfma_f32_16x16x32_bf16 v[212:215], v[252:255], v[64:67], v[212:215]
	s_waitcnt lgkmcnt(3)
	v_mfma_f32_16x16x32_bf16 v[52:55], v[216:219], v[52:55], 0
	s_waitcnt lgkmcnt(2)
	v_mfma_f32_16x16x32_bf16 v[52:55], v[220:223], v[56:59], v[52:55]
	s_waitcnt lgkmcnt(1)
	v_mfma_f32_16x16x32_bf16 v[52:55], v[224:227], v[60:63], v[52:55]
	s_waitcnt lgkmcnt(0)
	v_mfma_f32_16x16x32_bf16 v[52:55], v[228:231], v[64:67], v[52:55]
	s_cmp_lg_u32 s37, 1
	s_cselect_b64 s[72:73], -1, 0
	s_or_b64 s[76:77], s[72:73], s[58:59]
	v_add_f32_e32 v0, v143, v184
	s_and_b64 vcc, s[76:77], s[4:5]
	v_cndmask_b32_e32 v0, v142, v0, vcc
	v_add_f32_e32 v1, v144, v185
	s_and_b64 vcc, s[76:77], s[6:7]
	v_cndmask_b32_e32 v1, v142, v1, vcc
	v_add_f32_e32 v56, v145, v186
	s_and_b64 vcc, s[76:77], s[8:9]
	v_cndmask_b32_e32 v56, v142, v56, vcc
	v_add_f32_e32 v57, v146, v187
	s_and_b64 vcc, s[76:77], s[10:11]
	v_cndmask_b32_e32 v57, v142, v57, vcc
	v_add_f32_e32 v58, v147, v188
	s_or_b64 vcc, s[72:73], s[0:1]
	v_cndmask_b32_e32 v60, v142, v58, vcc
	v_add_f32_e32 v58, v148, v189
	v_cndmask_b32_e32 v61, v142, v58, vcc
	v_add_f32_e32 v58, v149, v190
	v_cndmask_b32_e32 v62, v142, v58, vcc
	v_add_f32_e32 v58, v150, v191
	v_cndmask_b32_e32 v63, v142, v58, vcc
	v_add_f32_e32 v58, v151, v192
	s_or_b64 vcc, s[72:73], s[60:61]
	v_cndmask_b32_e32 v64, v142, v58, vcc
	v_add_f32_e32 v58, v152, v193
	v_cndmask_b32_e32 v65, v142, v58, vcc
	v_add_f32_e32 v58, v155, v194
	v_cndmask_b32_e32 v66, v142, v58, vcc
	v_add_f32_e32 v58, v156, v195
	v_cndmask_b32_e32 v67, v142, v58, vcc
	v_add_f32_e32 v58, v157, v196
	s_or_b64 vcc, s[72:73], s[62:63]
	v_cndmask_b32_e32 v118, v142, v58, vcc
	v_add_f32_e32 v58, v158, v197
	v_cndmask_b32_e32 v120, v142, v58, vcc
	v_add_f32_e32 v58, v159, v198
	v_cndmask_b32_e32 v121, v142, v58, vcc
	v_add_f32_e32 v58, v160, v199
	v_cndmask_b32_e32 v185, v142, v58, vcc
	v_add_f32_e32 v58, v161, v200
	s_or_b64 vcc, s[72:73], s[34:35]
	s_mov_b32 s39, 0xff800000
	v_cndmask_b32_e32 v186, v142, v58, vcc
	v_add_f32_e32 v58, v162, v201
	v_max3_f32 v2, v0, s39, v1
	v_cndmask_b32_e32 v187, v142, v58, vcc
	v_add_f32_e32 v58, v163, v202
	v_max3_f32 v2, v2, v56, v57
	v_cndmask_b32_e32 v188, v142, v58, vcc
	v_add_f32_e32 v58, v164, v203
	v_max3_f32 v2, v2, v60, v61
	v_cndmask_b32_e32 v189, v142, v58, vcc
	v_add_f32_e32 v58, v165, v204
	s_or_b64 vcc, s[72:73], s[64:65]
	v_max3_f32 v2, v2, v62, v63
	v_cndmask_b32_e32 v190, v142, v58, vcc
	v_add_f32_e32 v58, v166, v205
	v_max3_f32 v2, v2, v64, v65
	v_cndmask_b32_e32 v191, v142, v58, vcc
	v_add_f32_e32 v58, v167, v206
	v_max3_f32 v2, v2, v66, v67
	v_cndmask_b32_e32 v192, v142, v58, vcc
	v_add_f32_e32 v58, v168, v207
	v_max3_f32 v2, v2, v118, v120
	v_cndmask_b32_e32 v193, v142, v58, vcc
	v_add_f32_e32 v58, v169, v208
	s_or_b64 vcc, s[72:73], s[48:49]
	v_max3_f32 v2, v2, v121, v185
	v_cndmask_b32_e32 v194, v142, v58, vcc
	v_add_f32_e32 v58, v170, v209
	v_max3_f32 v2, v2, v186, v187
	v_cndmask_b32_e32 v195, v142, v58, vcc
	v_add_f32_e32 v58, v171, v210
	v_max3_f32 v2, v2, v188, v189
	v_cndmask_b32_e32 v196, v142, v58, vcc
	v_add_f32_e32 v58, v172, v211
	v_max3_f32 v2, v2, v190, v191
	v_cndmask_b32_e32 v197, v142, v58, vcc
	v_add_f32_e32 v58, v173, v212
	s_or_b64 vcc, s[72:73], s[20:21]
	v_max3_f32 v2, v2, v192, v193
	v_cndmask_b32_e32 v198, v142, v58, vcc
	v_add_f32_e32 v58, v174, v213
	v_max3_f32 v2, v2, v194, v195
	v_cndmask_b32_e32 v199, v142, v58, vcc
	v_add_f32_e32 v58, v175, v214
	v_add_f32_e32 v52, v177, v52
	v_max3_f32 v2, v2, v196, v197
	v_cndmask_b32_e32 v200, v142, v58, vcc
	v_add_f32_e32 v58, v176, v215
	v_cndmask_b32_e64 v202, v52, v142, s[12:13]
	v_add_f32_e32 v52, v178, v53
	v_max3_f32 v2, v2, v198, v199
	v_cndmask_b32_e32 v201, v142, v58, vcc
	v_cndmask_b32_e64 v203, v142, v52, s[14:15]
	v_add_f32_e32 v52, v179, v54
	v_max3_f32 v2, v2, v200, v201
	v_cndmask_b32_e64 v204, v52, v142, s[16:17]
	v_add_f32_e32 v52, v180, v55
	v_max3_f32 v2, v2, v202, v203
	v_cndmask_b32_e64 v205, v52, v142, s[18:19]
	v_max3_f32 v2, v2, v204, v205
	ds_bpermute_b32 v52, v139, v2
	s_add_i32 vcc_hi, s25, s74
	s_add_i32 s39, s70, s75
	s_add_i32 s71, s44, s36
	s_add_i32 s67, s66, s67
	s_waitcnt lgkmcnt(0)
	v_max_f32_e32 v52, v52, v52
	v_max_f32_e32 v2, v2, v52
	ds_bpermute_b32 v52, v140, v2
	s_add_i32 s36, s45, s52
	s_add_i32 s75, s69, s51
	s_add_i32 s55, s25, s55
	s_add_i32 vcc_lo, s46, s53
	s_waitcnt lgkmcnt(0)
; __device__ __forceinline__ unsigned cvtpk(float lo, float hi) { return pg8::cvt_pk_bf16(lo, hi); }
; #define ATT_LOADV(buf, cc, k0_, k1_) do { _Pragma("unroll") for (int ks_ = (k0_); ks_ < (k1_); ++ks_) { const int t0_ = w + 2 * ks_, t1_ = t0_ + 1; \
;             vf[buf][2 * ks_] = trd(lds + VBASE + ((t0_ >> 3) ? cur : prv) * SLOTB + (t0_ & 7) * 4096 + voff[cc]); \
;             vf[buf][2 * ks_ + 1] = trd(lds + VBASE + ((t1_ >> 3) ? cur : prv) * SLOTB + (t1_ & 7) * 4096 + voff[cc]); } } while (0)
; #define ATT_LOADV8(buf, cc) do { const int t8_ = w + 8; vf[buf][8] = trd(lds + VBASE + cur * SLOTB + (t8_ & 7) * 4096 + voff[cc]); } while (0)
; __device__ __forceinline__ void segment(LAS unsigned char* lds, const bf16* __restrict__ QKV, bf16* __restrict__ Og, float* __restrict__ L2, int bl, int g, int h, int r, int dil, int n0, int cnt, int tid) {
;     ...
;         float den = 0.f; unsigned pk[9][2];
; #pragma unroll
;         for (int kt = 0; kt < 9; ++kt) { const float p0 = __builtin_amdgcn_exp2f(sc[kt][0] - mx), p1 = __builtin_amdgcn_exp2f(sc[kt][1] - mx), p2 = __builtin_amdgcn_exp2f(sc[kt][2] - mx), p3 = __builtin_amdgcn_exp2f(sc[kt][3] - mx);
;             den += (p0 + p1) + (p2 + p3); pk[kt][0] = cvtpk(p0, p1); pk[kt][1] = cvtpk(p2, p3); }
;         den += __shfl_xor(den, 16); den += __shfl_xor(den, 32);
;         const float rden = __builtin_amdgcn_rcpf(den);
;         const size_t orow = rowbase + (size_t)(128 * n + 16 * w + lq) * dil;
;         bf16* op16 = Og + ((size_t)g * MH + orow) * 1024 + h * 128 + ((gq & 2) ? 16 + 8 * (gq - 2) : 8 * gq); v2u wprev = {0u, 0u};
;         s16x4 vf[2][9];
;     ...
;         ATT_LOADV(0, 0, 0, 2); ATT_LOADV(0, 0, 2, 4); ATT_LOADV8(0, 0);
; #pragma unroll
;         for (int c = 0; c < 8; ++c) { f32x4 a = {0.f, 0.f, 0.f, 0.f};
;             if (c < 7) ATT_LOADV((c + 1) & 1, c + 1, 0, 2);
;             ATT_PVMMA(0); ATT_PVMMA(1);
;             __builtin_amdgcn_sched_barrier(0);
;             if (c < 7) { ATT_LOADV((c + 1) & 1, c + 1, 2, 4); ATT_LOADV8((c + 1) & 1, c + 1); }
;             ATT_PVMMA(2); ATT_PVMMA(3);
;             { const s16x4 v8 = vf[c & 1][8];
;               const bf16x8 A8 = {v8[0], v8[1], v8[2], v8[3], 0, 0, 0, 0}; const v4u bw8 = {pk[8][0], pk[8][1], 0u, 0u};
;               a = __builtin_amdgcn_mfma_f32_16x16x32_bf16(A8, __builtin_bit_cast(bf16x8, bw8), a, 0, 0, 0); }
	v_max_f32_e32 v52, v52, v52
	v_max_f32_e32 v184, v2, v52
	v_sub_f32_e32 v1, v1, v184
	v_sub_f32_e32 v0, v0, v184
	v_exp_f32_e32 v52, v1
	v_sub_f32_e32 v1, v56, v184
	v_sub_f32_e32 v2, v57, v184
	v_exp_f32_e32 v0, v0
	v_exp_f32_e32 v1, v1
	v_exp_f32_e32 v53, v2
	v_sub_f32_e32 v2, v60, v184
	s_add_i32 s74, s68, s50
	v_add_u32_e32 v210, s71, v129
	v_pk_add_f32 v[54:55], v[0:1], v[52:53]
	v_cvt_pk_bf16_f32 v52, v0, v52
	v_pk_add_f32 v[58:59], v[54:55], v[54:55] op_sel_hi:[0,1]
	v_exp_f32_e32 v54, v2
	v_sub_f32_e32 v2, v61, v184
	v_exp_f32_e32 v55, v2
	v_sub_f32_e32 v2, v62, v184
	v_exp_f32_e32 v60, v2
	v_sub_f32_e32 v2, v63, v184
	v_exp_f32_e32 v61, v2
	v_sub_f32_e32 v2, v65, v184
	v_exp_f32_e32 v56, v2
	v_sub_f32_e32 v2, v66, v184
	v_sub_f32_e32 v0, v64, v184
	v_exp_f32_e32 v58, v2
	v_sub_f32_e32 v2, v67, v184
	v_exp_f32_e32 v0, v0
	v_exp_f32_e32 v2, v2
	v_cvt_pk_bf16_f32 v53, v1, v53
	v_add_f32_e32 v1, v54, v55
	v_add_f32_e32 v57, v60, v61
	v_cvt_pk_bf16_f32 v54, v54, v55
	v_cvt_pk_bf16_f32 v55, v60, v61
	v_pk_add_f32 v[60:61], v[0:1], v[56:57]
	v_pk_add_f32 v[62:63], v[58:59], v[2:3]
	v_sub_f32_e32 v1, v118, v184
	v_pk_add_f32 v[60:61], v[60:61], v[62:63]
	v_exp_f32_e32 v62, v1
	v_sub_f32_e32 v1, v120, v184
	v_exp_f32_e32 v64, v1
	v_sub_f32_e32 v1, v121, v184
	v_exp_f32_e32 v63, v1
	v_sub_f32_e32 v1, v185, v184
	v_exp_f32_e32 v65, v1
	v_cvt_pk_bf16_f32 v56, v0, v56
	v_cvt_pk_bf16_f32 v57, v58, v2
	v_sub_f32_e32 v2, v187, v184
	v_pk_add_f32 v[0:1], v[62:63], v[64:65]
	v_sub_f32_e32 v58, v188, v184
	v_pk_add_f32 v[0:1], v[0:1], v[0:1] op_sel_hi:[0,1]
	v_sub_f32_e32 v0, v186, v184
	v_pk_add_f32 v[66:67], v[60:61], v[60:61] op_sel_hi:[0,1]
	v_exp_f32_e32 v0, v0
	v_exp_f32_e32 v2, v2
	v_exp_f32_e32 v61, v58
	v_sub_f32_e32 v58, v189, v184
	v_exp_f32_e32 v66, v58
	v_cvt_pk_bf16_f32 v59, v63, v65
	v_add_f32_e32 v63, v0, v2
	v_cvt_pk_bf16_f32 v60, v0, v2
	v_sub_f32_e32 v0, v190, v184
	v_sub_f32_e32 v2, v193, v184
	v_cvt_pk_bf16_f32 v58, v62, v64
	v_add_f32_e32 v65, v61, v66
	v_cvt_pk_bf16_f32 v61, v61, v66
	v_exp_f32_e32 v62, v0
	v_sub_f32_e32 v0, v191, v184
	v_exp_f32_e32 v66, v2
	v_sub_f32_e32 v2, v194, v184
	v_exp_f32_e32 v64, v0
	v_sub_f32_e32 v0, v192, v184
	v_exp_f32_e32 v186, v2
	v_sub_f32_e32 v2, v195, v184
	v_exp_f32_e32 v0, v0
	v_exp_f32_e32 v188, v2
	v_sub_f32_e32 v2, v196, v184
	v_exp_f32_e32 v187, v2
	v_sub_f32_e32 v2, v197, v184
	v_exp_f32_e32 v189, v2
	v_pk_add_f32 v[120:121], v[62:63], v[64:65]
	v_sub_f32_e32 v63, v200, v184
	v_pk_add_f32 v[190:191], v[0:1], v[66:67]
	v_exp_f32_e32 v67, v63
	v_sub_f32_e32 v63, v201, v184
	v_exp_f32_e32 v118, v63
	v_sub_f32_e32 v63, v202, v184
	v_pk_add_f32 v[120:121], v[120:121], v[190:191]
	v_pk_add_f32 v[190:191], v[186:187], v[188:189]
	v_exp_f32_e32 v192, v63
	v_sub_f32_e32 v63, v203, v184
	v_pk_add_f32 v[190:191], v[190:191], v[190:191] op_sel_hi:[0,1]
	v_sub_f32_e32 v1, v198, v184
	v_sub_f32_e32 v2, v199, v184
	v_exp_f32_e32 v194, v63
	v_sub_f32_e32 v63, v204, v184
	v_pk_add_f32 v[120:121], v[120:121], v[120:121] op_sel_hi:[0,1]
	v_exp_f32_e32 v1, v1
	v_exp_f32_e32 v2, v2
	v_exp_f32_e32 v190, v63
	v_sub_f32_e32 v63, v205, v184
	v_exp_f32_e32 v120, v63
	v_add_f32_e32 v193, v1, v2
	v_add_f32_e32 v195, v67, v118
	v_pk_add_f32 v[196:197], v[192:193], v[194:195]
	v_pk_add_f32 v[198:199], v[190:191], v[120:121]
	v_cvt_pk_bf16_f32 v63, v0, v66
	v_pk_add_f32 v[196:197], v[196:197], v[198:199]
	v_cvt_pk_bf16_f32 v66, v1, v2
	v_add_f32_e32 v121, v196, v197
	ds_bpermute_b32 v185, v139, v121
	v_add_u32_e32 v2, vcc_hi, v128
	v_cvt_pk_bf16_f32 v62, v62, v64
	v_cvt_pk_bf16_f32 v64, v186, v188
	v_cvt_pk_bf16_f32 v65, v187, v189
	s_waitcnt lgkmcnt(0)
	v_add_f32_e32 v121, v121, v185
	ds_bpermute_b32 v185, v140, v121
	v_cvt_pk_bf16_f32 v67, v67, v118
	v_cvt_pk_bf16_f32 v0, v192, v194
	v_cvt_pk_bf16_f32 v1, v190, v120
	v_add_u32_e32 v118, s39, v128
	s_waitcnt lgkmcnt(0)
	v_add_f32_e32 v185, v121, v185
	v_add_u32_e32 v120, s71, v128
	v_add_u32_e32 v121, s67, v128
	ds_read_b64_tr_b16 v[186:187], v2
	ds_read_b64_tr_b16 v[188:189], v118
	ds_read_b64_tr_b16 v[190:191], v120
	ds_read_b64_tr_b16 v[192:193], v121
	v_add_u32_e32 v2, s36, v128
	v_add_u32_e32 v200, s75, v128
	v_add_u32_e32 v202, s55, v128
	v_add_u32_e32 v120, vcc_lo, v128
	v_add_u32_e32 v121, s74, v128
	ds_read_b64_tr_b16 v[194:195], v2
	ds_read_b64_tr_b16 v[196:197], v120
	ds_read_b64_tr_b16 v[198:199], v121
	ds_read_b64_tr_b16 v[200:201], v200
	v_add_u32_e32 v204, vcc_hi, v129
	v_add_u32_e32 v205, s39, v129
	ds_read_b64_tr_b16 v[202:203], v202
	ds_read_b64_tr_b16 v[206:207], v204
	ds_read_b64_tr_b16 v[208:209], v205
	ds_read_b64_tr_b16 v[210:211], v210
	v_add_u32_e32 v204, s67, v129
	s_waitcnt lgkmcnt(10)
	v_mfma_f32_16x16x32_bf16 v[186:189], v[186:189], v[52:55], 0
	ds_read_b64_tr_b16 v[212:213], v204
	v_rcp_f32_e32 v118, v185
	v_lshl_add_u64 v[120:121], v[104:105], 0, s[56:57]
	v_mov_b32_e32 v2, v3
	s_waitcnt lgkmcnt(9)
	v_mfma_f32_16x16x32_bf16 v[186:189], v[190:193], v[56:59], v[186:189]
	s_waitcnt lgkmcnt(7)
	v_mfma_f32_16x16x32_bf16 v[186:189], v[194:197], v[60:63], v[186:189]
	v_mov_b32_e32 v204, v3
	v_mov_b32_e32 v205, v3
	v_add_u32_e32 v190, s36, v129
	s_waitcnt lgkmcnt(5)
	v_mfma_f32_16x16x32_bf16 v[186:189], v[198:201], v[64:67], v[186:189]
	v_add_u32_e32 v192, vcc_lo, v129
	v_add_u32_e32 v194, s74, v129
	v_add_u32_e32 v196, s75, v129
	ds_read_b64_tr_b16 v[190:191], v190
	ds_read_b64_tr_b16 v[192:193], v192
	ds_read_b64_tr_b16 v[194:195], v194
	ds_read_b64_tr_b16 v[196:197], v196
	v_add_u32_e32 v198, s55, v129
	s_waitcnt lgkmcnt(8)
; __device__ __forceinline__ unsigned cvtpk(float lo, float hi) { return pg8::cvt_pk_bf16(lo, hi); }
; #define ATT_LOADV(buf, cc, k0_, k1_) do { _Pragma("unroll") for (int ks_ = (k0_); ks_ < (k1_); ++ks_) { const int t0_ = w + 2 * ks_, t1_ = t0_ + 1; \
;             vf[buf][2 * ks_] = trd(lds + VBASE + ((t0_ >> 3) ? cur : prv) * SLOTB + (t0_ & 7) * 4096 + voff[cc]); \
;             vf[buf][2 * ks_ + 1] = trd(lds + VBASE + ((t1_ >> 3) ? cur : prv) * SLOTB + (t1_ & 7) * 4096 + voff[cc]); } } while (0)
; #define ATT_LOADV8(buf, cc) do { const int t8_ = w + 8; vf[buf][8] = trd(lds + VBASE + cur * SLOTB + (t8_ & 7) * 4096 + voff[cc]); } while (0)
; __device__ __forceinline__ void segment(LAS unsigned char* lds, const bf16* __restrict__ QKV, bf16* __restrict__ Og, float* __restrict__ L2, int bl, int g, int h, int r, int dil, int n0, int cnt, int tid) {
;     ...
;         for (int c = 0; c < 8; ++c) { f32x4 a = {0.f, 0.f, 0.f, 0.f};
;             if (c < 7) ATT_LOADV((c + 1) & 1, c + 1, 0, 2);
;             ATT_PVMMA(0); ATT_PVMMA(1);
;             __builtin_amdgcn_sched_barrier(0);
;             if (c < 7) { ATT_LOADV((c + 1) & 1, c + 1, 2, 4); ATT_LOADV8((c + 1) & 1, c + 1); }
;             ATT_PVMMA(2); ATT_PVMMA(3);
;             { const s16x4 v8 = vf[c & 1][8];
;               const bf16x8 A8 = {v8[0], v8[1], v8[2], v8[3], 0, 0, 0, 0}; const v4u bw8 = {pk[8][0], pk[8][1], 0u, 0u};
;               a = __builtin_amdgcn_mfma_f32_16x16x32_bf16(A8, __builtin_bit_cast(bf16x8, bw8), a, 0, 0, 0); }
;             v2u wv; wv.x = cvtpk(a[0] * rden, a[1] * rden); wv.y = cvtpk(a[2] * rden, a[3] * rden);
;             if (c & 1) {
;                 const auto rx = __builtin_amdgcn_permlane32_swap(wprev.x, wv.x, false, false); const auto ry = __builtin_amdgcn_permlane32_swap(wprev.y, wv.y, false, false);
;                 v4u o4; o4.x = rx[0]; o4.y = ry[0]; o4.z = rx[1]; o4.w = ry[1];
;                 *(v4u*)(op16 + 32 * (c >> 1)) = o4; }
;             else wprev = wv;
;             __builtin_amdgcn_sched_barrier(0); }
	v_mfma_f32_16x16x32_bf16 v[186:189], v[202:205], v[0:3], v[186:189]
	ds_read_b64_tr_b16 v[198:199], v198
	s_nop 6
	v_pk_mul_f32 v[188:189], v[118:119], v[188:189] op_sel_hi:[0,1]
	v_pk_mul_f32 v[186:187], v[118:119], v[186:187] op_sel_hi:[0,1]
	v_cvt_pk_bf16_f32 v189, v188, v189
	v_cvt_pk_bf16_f32 v188, v186, v187
	v_add_u32_e32 v186, vcc_hi, v130
	v_add_u32_e32 v214, s71, v130
	v_add_u32_e32 v216, s67, v130
	v_add_u32_e32 v187, s39, v130
	s_waitcnt lgkmcnt(7)
	v_mfma_f32_16x16x32_bf16 v[200:203], v[206:209], v[52:55], 0
	ds_read_b64_tr_b16 v[204:205], v186
	ds_read_b64_tr_b16 v[206:207], v187
	ds_read_b64_tr_b16 v[214:215], v214
	ds_read_b64_tr_b16 v[216:217], v216
	s_waitcnt lgkmcnt(9)
	v_mfma_f32_16x16x32_bf16 v[200:203], v[210:213], v[56:59], v[200:203]
	s_waitcnt lgkmcnt(7)
	v_mfma_f32_16x16x32_bf16 v[190:193], v[190:193], v[60:63], v[200:203]
	v_add_u32_e32 v186, s36, v130
	v_add_u32_e32 v187, vcc_lo, v130
	s_nop 3
	v_mov_b32_e32 v200, v3
	v_mov_b32_e32 v201, v3
	s_waitcnt lgkmcnt(5)
	v_mfma_f32_16x16x32_bf16 v[190:193], v[194:197], v[64:67], v[190:193]
	v_add_u32_e32 v202, s74, v130
	v_add_u32_e32 v203, s75, v130
	ds_read_b64_tr_b16 v[194:195], v186
	ds_read_b64_tr_b16 v[196:197], v187
	ds_read_b64_tr_b16 v[208:209], v202
	ds_read_b64_tr_b16 v[210:211], v203
	s_waitcnt lgkmcnt(8)
	v_mfma_f32_16x16x32_bf16 v[198:201], v[198:201], v[0:3], v[190:193]
	v_add_u32_e32 v186, s55, v130
	ds_read_b64_tr_b16 v[186:187], v186
	s_nop 5
	v_pk_mul_f32 v[190:191], v[118:119], v[200:201] op_sel_hi:[0,1]
	v_pk_mul_f32 v[192:193], v[118:119], v[198:199] op_sel_hi:[0,1]
	v_cvt_pk_bf16_f32 v191, v190, v191
	v_cvt_pk_bf16_f32 v190, v192, v193
	s_nop 1
	v_permlane32_swap_b32_e32 v188, v190
	v_permlane32_swap_b32_e32 v189, v191
	global_store_dwordx4 v[120:121], v[188:191], off
	v_add_u32_e32 v192, vcc_hi, v131
	v_add_u32_e32 v202, s71, v131
	v_add_u32_e32 v193, s39, v131
	v_add_u32_e32 v212, s67, v131
	s_waitcnt lgkmcnt(7)
	v_mfma_f32_16x16x32_bf16 v[188:191], v[204:207], v[52:55], 0
	ds_read_b64_tr_b16 v[198:199], v192
	ds_read_b64_tr_b16 v[200:201], v193
	ds_read_b64_tr_b16 v[202:203], v202
	ds_read_b64_tr_b16 v[204:205], v212
	s_waitcnt lgkmcnt(9)
	v_mfma_f32_16x16x32_bf16 v[188:191], v[214:217], v[56:59], v[188:191]
	s_waitcnt lgkmcnt(7)
	v_mfma_f32_16x16x32_bf16 v[190:193], v[194:197], v[60:63], v[188:191]
	v_add_u32_e32 v206, s36, v131
	v_add_u32_e32 v207, vcc_lo, v131
	v_add_u32_e32 v212, s74, v131
	s_nop 2
	v_mov_b32_e32 v188, v3
	v_mov_b32_e32 v189, v3
	s_waitcnt lgkmcnt(5)
	v_mfma_f32_16x16x32_bf16 v[190:193], v[208:211], v[64:67], v[190:193]
	v_add_u32_e32 v213, s75, v131
	ds_read_b64_tr_b16 v[194:195], v206
	ds_read_b64_tr_b16 v[196:197], v207
	ds_read_b64_tr_b16 v[206:207], v212
	ds_read_b64_tr_b16 v[208:209], v213
	v_add_u32_e32 v210, s55, v131
	s_waitcnt lgkmcnt(8)
	v_mfma_f32_16x16x32_bf16 v[186:189], v[186:189], v[0:3], v[190:193]
	ds_read_b64_tr_b16 v[210:211], v210
	s_nop 6
	v_pk_mul_f32 v[188:189], v[118:119], v[188:189] op_sel_hi:[0,1]
	v_pk_mul_f32 v[186:187], v[118:119], v[186:187] op_sel_hi:[0,1]
	v_cvt_pk_bf16_f32 v189, v188, v189
	v_cvt_pk_bf16_f32 v188, v186, v187
	v_add_u32_e32 v186, vcc_hi, v132
	v_add_u32_e32 v187, s39, v132
	v_add_u32_e32 v212, s71, v132
	v_add_u32_e32 v213, s67, v132
	s_waitcnt lgkmcnt(7)
	v_mfma_f32_16x16x32_bf16 v[190:193], v[198:201], v[52:55], 0
	ds_read_b64_tr_b16 v[198:199], v186
	ds_read_b64_tr_b16 v[200:201], v187
	ds_read_b64_tr_b16 v[214:215], v212
	ds_read_b64_tr_b16 v[216:217], v213
	s_waitcnt lgkmcnt(9)
	v_mfma_f32_16x16x32_bf16 v[190:193], v[202:205], v[56:59], v[190:193]
	s_waitcnt lgkmcnt(7)
	v_mfma_f32_16x16x32_bf16 v[190:193], v[194:197], v[60:63], v[190:193]
	v_mov_b32_e32 v212, v3
	v_mov_b32_e32 v213, v3
	v_add_u32_e32 v186, s36, v132
	s_waitcnt lgkmcnt(5)
	v_mfma_f32_16x16x32_bf16 v[190:193], v[206:209], v[64:67], v[190:193]
	v_add_u32_e32 v202, s74, v132
	v_add_u32_e32 v204, s75, v132
	v_add_u32_e32 v187, vcc_lo, v132
	ds_read_b64_tr_b16 v[194:195], v186
	ds_read_b64_tr_b16 v[196:197], v187
	ds_read_b64_tr_b16 v[202:203], v202
	ds_read_b64_tr_b16 v[204:205], v204
	s_waitcnt lgkmcnt(8)
	v_mfma_f32_16x16x32_bf16 v[206:209], v[210:213], v[0:3], v[190:193]
	v_add_u32_e32 v186, s55, v132
	ds_read_b64_tr_b16 v[186:187], v186
	s_nop 5
	v_pk_mul_f32 v[190:191], v[118:119], v[208:209] op_sel_hi:[0,1]
	v_pk_mul_f32 v[192:193], v[118:119], v[206:207] op_sel_hi:[0,1]
	v_cvt_pk_bf16_f32 v191, v190, v191
	v_cvt_pk_bf16_f32 v190, v192, v193
	s_nop 1
	v_permlane32_swap_b32_e32 v188, v190
	v_permlane32_swap_b32_e32 v189, v191
	global_store_dwordx4 v[120:121], v[188:191], off offset:64
	v_add_u32_e32 v192, vcc_hi, v133
	v_add_u32_e32 v206, s71, v133
	v_add_u32_e32 v208, s67, v133
	v_add_u32_e32 v193, s39, v133
	s_waitcnt lgkmcnt(7)
	v_mfma_f32_16x16x32_bf16 v[188:191], v[198:201], v[52:55], 0
	ds_read_b64_tr_b16 v[198:199], v192
	ds_read_b64_tr_b16 v[200:201], v193
	ds_read_b64_tr_b16 v[206:207], v206
	ds_read_b64_tr_b16 v[208:209], v208
	s_waitcnt lgkmcnt(9)
; __device__ __forceinline__ unsigned cvtpk(float lo, float hi) { return pg8::cvt_pk_bf16(lo, hi); }
; #define ATT_LOADV(buf, cc, k0_, k1_) do { _Pragma("unroll") for (int ks_ = (k0_); ks_ < (k1_); ++ks_) { const int t0_ = w + 2 * ks_, t1_ = t0_ + 1; \
;             vf[buf][2 * ks_] = trd(lds + VBASE + ((t0_ >> 3) ? cur : prv) * SLOTB + (t0_ & 7) * 4096 + voff[cc]); \
;             vf[buf][2 * ks_ + 1] = trd(lds + VBASE + ((t1_ >> 3) ? cur : prv) * SLOTB + (t1_ & 7) * 4096 + voff[cc]); } } while (0)
; #define ATT_LOADV8(buf, cc) do { const int t8_ = w + 8; vf[buf][8] = trd(lds + VBASE + cur * SLOTB + (t8_ & 7) * 4096 + voff[cc]); } while (0)
; __device__ __forceinline__ void segment(LAS unsigned char* lds, const bf16* __restrict__ QKV, bf16* __restrict__ Og, float* __restrict__ L2, int bl, int g, int h, int r, int dil, int n0, int cnt, int tid) {
;     ...
;         for (int c = 0; c < 8; ++c) { f32x4 a = {0.f, 0.f, 0.f, 0.f};
;             if (c < 7) ATT_LOADV((c + 1) & 1, c + 1, 0, 2);
;             ATT_PVMMA(0); ATT_PVMMA(1);
;             __builtin_amdgcn_sched_barrier(0);
;             if (c < 7) { ATT_LOADV((c + 1) & 1, c + 1, 2, 4); ATT_LOADV8((c + 1) & 1, c + 1); }
;             ATT_PVMMA(2); ATT_PVMMA(3);
;             { const s16x4 v8 = vf[c & 1][8];
;               const bf16x8 A8 = {v8[0], v8[1], v8[2], v8[3], 0, 0, 0, 0}; const v4u bw8 = {pk[8][0], pk[8][1], 0u, 0u};
;               a = __builtin_amdgcn_mfma_f32_16x16x32_bf16(A8, __builtin_bit_cast(bf16x8, bw8), a, 0, 0, 0); }
;             v2u wv; wv.x = cvtpk(a[0] * rden, a[1] * rden); wv.y = cvtpk(a[2] * rden, a[3] * rden);
;             if (c & 1) {
;                 const auto rx = __builtin_amdgcn_permlane32_swap(wprev.x, wv.x, false, false); const auto ry = __builtin_amdgcn_permlane32_swap(wprev.y, wv.y, false, false);
;                 v4u o4; o4.x = rx[0]; o4.y = ry[0]; o4.z = rx[1]; o4.w = ry[1];
;                 *(v4u*)(op16 + 32 * (c >> 1)) = o4; }
;             else wprev = wv;
;             __builtin_amdgcn_sched_barrier(0); }
;     ...
;         if (gq == 0) L2[((size_t)g * MH + orow) * 8 + h] = mx + __builtin_amdgcn_logf(den);
	v_mfma_f32_16x16x32_bf16 v[188:191], v[214:217], v[56:59], v[188:191]
	s_waitcnt lgkmcnt(7)
	v_mfma_f32_16x16x32_bf16 v[190:193], v[194:197], v[60:63], v[188:191]
	v_add_u32_e32 v210, s36, v133
	v_add_u32_e32 v211, vcc_lo, v133
	v_add_u32_e32 v212, s74, v133
	s_nop 2
	v_mov_b32_e32 v188, v3
	v_mov_b32_e32 v189, v3
	s_waitcnt lgkmcnt(5)
	v_mfma_f32_16x16x32_bf16 v[190:193], v[202:205], v[64:67], v[190:193]
	v_add_u32_e32 v213, s75, v133
	ds_read_b64_tr_b16 v[194:195], v210
	ds_read_b64_tr_b16 v[196:197], v211
	ds_read_b64_tr_b16 v[202:203], v212
	ds_read_b64_tr_b16 v[204:205], v213
	v_add_u32_e32 v210, s55, v133
	s_waitcnt lgkmcnt(8)
	v_mfma_f32_16x16x32_bf16 v[186:189], v[186:189], v[0:3], v[190:193]
	ds_read_b64_tr_b16 v[210:211], v210
	s_nop 6
	v_pk_mul_f32 v[188:189], v[118:119], v[188:189] op_sel_hi:[0,1]
	v_pk_mul_f32 v[186:187], v[118:119], v[186:187] op_sel_hi:[0,1]
	v_cvt_pk_bf16_f32 v189, v188, v189
	v_cvt_pk_bf16_f32 v188, v186, v187
	v_add_u32_e32 v186, vcc_hi, v134
	v_add_u32_e32 v187, s39, v134
	v_add_u32_e32 v212, s71, v134
	v_add_u32_e32 v213, s67, v134
	s_waitcnt lgkmcnt(7)
	v_mfma_f32_16x16x32_bf16 v[190:193], v[198:201], v[52:55], 0
	ds_read_b64_tr_b16 v[198:199], v186
	ds_read_b64_tr_b16 v[200:201], v187
	ds_read_b64_tr_b16 v[214:215], v212
	ds_read_b64_tr_b16 v[216:217], v213
	s_waitcnt lgkmcnt(9)
	v_mfma_f32_16x16x32_bf16 v[190:193], v[206:209], v[56:59], v[190:193]
	s_waitcnt lgkmcnt(7)
	v_mfma_f32_16x16x32_bf16 v[190:193], v[194:197], v[60:63], v[190:193]
	v_mov_b32_e32 v212, v3
	v_mov_b32_e32 v213, v3
	v_add_u32_e32 v186, s36, v134
	s_waitcnt lgkmcnt(5)
	v_mfma_f32_16x16x32_bf16 v[190:193], v[202:205], v[64:67], v[190:193]
	v_add_u32_e32 v206, s74, v134
	v_add_u32_e32 v207, s75, v134
	v_add_u32_e32 v187, vcc_lo, v134
	ds_read_b64_tr_b16 v[194:195], v186
	ds_read_b64_tr_b16 v[196:197], v187
	ds_read_b64_tr_b16 v[202:203], v206
	ds_read_b64_tr_b16 v[204:205], v207
	s_waitcnt lgkmcnt(8)
	v_mfma_f32_16x16x32_bf16 v[206:209], v[210:213], v[0:3], v[190:193]
	v_add_u32_e32 v186, s55, v134
	ds_read_b64_tr_b16 v[186:187], v186
	s_nop 5
	v_pk_mul_f32 v[190:191], v[118:119], v[208:209] op_sel_hi:[0,1]
	v_pk_mul_f32 v[192:193], v[118:119], v[206:207] op_sel_hi:[0,1]
	v_cvt_pk_bf16_f32 v191, v190, v191
	v_cvt_pk_bf16_f32 v190, v192, v193
	s_nop 1
	v_permlane32_swap_b32_e32 v188, v190
	v_permlane32_swap_b32_e32 v189, v191
	global_store_dwordx4 v[120:121], v[188:191], off offset:128
	v_add_u32_e32 v192, vcc_hi, v135
	v_add_u32_e32 v206, s71, v135
	v_add_u32_e32 v208, s67, v135
	v_add_u32_e32 v193, s39, v135
	s_waitcnt lgkmcnt(7)
	v_mfma_f32_16x16x32_bf16 v[188:191], v[198:201], v[52:55], 0
	ds_read_b64_tr_b16 v[198:199], v192
	ds_read_b64_tr_b16 v[200:201], v193
	ds_read_b64_tr_b16 v[206:207], v206
	ds_read_b64_tr_b16 v[208:209], v208
	s_waitcnt lgkmcnt(9)
	v_mfma_f32_16x16x32_bf16 v[188:191], v[214:217], v[56:59], v[188:191]
	s_waitcnt lgkmcnt(7)
	v_mfma_f32_16x16x32_bf16 v[190:193], v[194:197], v[60:63], v[188:191]
	v_add_u32_e32 v210, s36, v135
	v_add_u32_e32 v211, vcc_lo, v135
	v_add_u32_e32 v212, s74, v135
	s_nop 2
	v_mov_b32_e32 v188, v3
	v_mov_b32_e32 v189, v3
	s_waitcnt lgkmcnt(5)
	v_mfma_f32_16x16x32_bf16 v[190:193], v[202:205], v[64:67], v[190:193]
	v_add_u32_e32 v213, s75, v135
	ds_read_b64_tr_b16 v[194:195], v210
	ds_read_b64_tr_b16 v[196:197], v211
	ds_read_b64_tr_b16 v[202:203], v212
	ds_read_b64_tr_b16 v[204:205], v213
	v_add_u32_e32 v210, s55, v135
	s_waitcnt lgkmcnt(8)
	v_mfma_f32_16x16x32_bf16 v[186:189], v[186:189], v[0:3], v[190:193]
	ds_read_b64_tr_b16 v[210:211], v210
	s_nop 6
	v_pk_mul_f32 v[188:189], v[118:119], v[188:189] op_sel_hi:[0,1]
	v_pk_mul_f32 v[186:187], v[118:119], v[186:187] op_sel_hi:[0,1]
	v_cvt_pk_bf16_f32 v189, v188, v189
	v_cvt_pk_bf16_f32 v188, v186, v187
	s_waitcnt lgkmcnt(7)
	v_mfma_f32_16x16x32_bf16 v[52:55], v[198:201], v[52:55], 0
	s_waitcnt lgkmcnt(5)
	v_mfma_f32_16x16x32_bf16 v[52:55], v[206:209], v[56:59], v[52:55]
	s_waitcnt lgkmcnt(3)
	v_mfma_f32_16x16x32_bf16 v[52:55], v[194:197], v[60:63], v[52:55]
	v_mov_b32_e32 v212, v3
	v_mov_b32_e32 v213, v3
	s_waitcnt lgkmcnt(1)
	v_mfma_f32_16x16x32_bf16 v[52:55], v[202:205], v[64:67], v[52:55]
	s_waitcnt lgkmcnt(0)
	v_mfma_f32_16x16x32_bf16 v[52:55], v[210:213], v[0:3], v[52:55]
	s_nop 7
	v_pk_mul_f32 v[0:1], v[118:119], v[54:55] op_sel_hi:[0,1]
	v_pk_mul_f32 v[52:53], v[118:119], v[52:53] op_sel_hi:[0,1]
	v_cvt_pk_bf16_f32 v191, v0, v1
	v_cvt_pk_bf16_f32 v190, v52, v53
	s_nop 1
	v_permlane32_swap_b32_e32 v188, v190
	v_permlane32_swap_b32_e32 v189, v191
	global_store_dwordx4 v[120:121], v[188:191], off offset:192
	s_and_saveexec_b64 vcc, s[2:3]
	s_cbranch_execz .LBB0_295
	v_log_f32_e32 v0, v185
	s_nop 0
	v_add_f32_e32 v0, v184, v0
	global_store_dword v[102:103], v0, off
	s_branch .LBB0_295

; #define LAS __attribute__((address_space(3)))
; __device__ __forceinline__ void segment(LAS unsigned char* lds, const bf16* __restrict__ QKV, bf16* __restrict__ Og, float* __restrict__ L2, int bl, int g, int h, int r, int dil, int n0, int cnt, int tid) {
;     ...
;         { bf16x8 kf[2][4];
;             { const int slot0 = (w >> 3) ? cur : prv; const LAS unsigned char* kb0 = lds + slot0 * SLOTB + (w & 7) * 4096;
; #pragma unroll
;               for (int s = 0; s < 4; ++s) kf[0][s] = *(const LAS bf16x8*)(kb0 + koff[s]); }
; #pragma unroll
;             for (int kt = 0; kt < 9; ++kt) {
;                 if (kt < 8) { const int tt = w + kt + 1; const int slot = (tt >> 3) ? cur : prv; const LAS unsigned char* kb = lds + slot * SLOTB + (tt & 7) * 4096;
; #pragma unroll
;                     for (int s = 0; s < 4; ++s) kf[(kt + 1) & 1][s] = *(const LAS bf16x8*)(kb + koff[s]); }
;                 f32x4 a = {0.f, 0.f, 0.f, 0.f};
; #pragma unroll
;                 for (int s = 0; s < 4; ++s) a = __builtin_amdgcn_mfma_f32_16x16x32_bf16(kf[kt & 1][s], qf[s], a, 0, 0, 0);
;                 sc[kt] = a;
;                 __builtin_amdgcn_sched_barrier(0); } }
.LBB0_452:
	s_xor_b32 s69, s51, 1
	s_and_b64 s[52:53], s[42:43], exec
	s_cselect_b32 s36, s69, s51
	s_lshl_b32 s72, s36, 15
	s_add_i32 s36, s24, s72
	v_add_u32_e32 v0, s36, v123
	v_add_u32_e32 v1, s36, v124
	ds_read_b128 v[218:221], v0
	ds_read_b128 v[222:225], v1
	v_add_u32_e32 v0, s36, v125
	v_add_u32_e32 v1, s36, v126
	ds_read_b128 v[226:229], v0
	ds_read_b128 v[230:233], v1
	s_and_b64 s[52:53], s[82:83], exec
	s_cselect_b32 s36, s69, s51
	s_lshl_b32 s73, s36, 15
	s_add_i32 s36, s26, s73
	v_add_u32_e32 v0, s36, v123
	v_add_u32_e32 v1, s36, v124
	ds_read_b128 v[240:243], v0
	ds_read_b128 v[244:247], v1
	v_add_u32_e32 v0, s36, v125
	v_add_u32_e32 v1, s36, v126
	ds_read_b128 v[248:251], v0
	ds_read_b128 v[252:255], v1
	s_waitcnt lgkmcnt(7)
	v_mfma_f32_16x16x32_bf16 v[186:189], v[218:221], v[52:55], 0
	s_waitcnt lgkmcnt(6)
	v_mfma_f32_16x16x32_bf16 v[186:189], v[222:225], v[56:59], v[186:189]
	s_waitcnt lgkmcnt(5)
	v_mfma_f32_16x16x32_bf16 v[186:189], v[226:229], v[60:63], v[186:189]
	s_waitcnt lgkmcnt(4)
	v_mfma_f32_16x16x32_bf16 v[186:189], v[230:233], v[64:67], v[186:189]
	s_and_b64 s[52:53], s[84:85], exec
	s_cselect_b32 s36, s69, s51
	s_lshl_b32 s36, s36, 15
	s_add_i32 s49, s27, s36
	v_add_u32_e32 v0, s49, v123
	v_add_u32_e32 v1, s49, v124
	ds_read_b128 v[218:221], v0
	ds_read_b128 v[222:225], v1
	v_add_u32_e32 v0, s49, v125
	v_add_u32_e32 v1, s49, v126
	ds_read_b128 v[226:229], v0
	ds_read_b128 v[230:233], v1
	s_waitcnt lgkmcnt(7)
	v_mfma_f32_16x16x32_bf16 v[190:193], v[240:243], v[52:55], 0
	s_waitcnt lgkmcnt(6)
	v_mfma_f32_16x16x32_bf16 v[190:193], v[244:247], v[56:59], v[190:193]
	s_waitcnt lgkmcnt(5)
	v_mfma_f32_16x16x32_bf16 v[190:193], v[248:251], v[60:63], v[190:193]
	s_waitcnt lgkmcnt(4)
	v_mfma_f32_16x16x32_bf16 v[190:193], v[252:255], v[64:67], v[190:193]
	s_and_b64 s[52:53], s[86:87], exec
	s_cselect_b32 s49, s69, s51
	s_lshl_b32 s49, s49, 15
	s_add_i32 s50, s28, s49
	v_add_u32_e32 v0, s50, v123
	v_add_u32_e32 v1, s50, v124
	ds_read_b128 v[240:243], v0
	ds_read_b128 v[244:247], v1
	v_add_u32_e32 v0, s50, v125
	v_add_u32_e32 v1, s50, v126
	ds_read_b128 v[248:251], v0
	ds_read_b128 v[252:255], v1
	s_waitcnt lgkmcnt(7)
	v_mfma_f32_16x16x32_bf16 v[194:197], v[218:221], v[52:55], 0
	s_waitcnt lgkmcnt(6)
	v_mfma_f32_16x16x32_bf16 v[194:197], v[222:225], v[56:59], v[194:197]
	s_waitcnt lgkmcnt(5)
	v_mfma_f32_16x16x32_bf16 v[194:197], v[226:229], v[60:63], v[194:197]
	s_waitcnt lgkmcnt(4)
	v_mfma_f32_16x16x32_bf16 v[194:197], v[230:233], v[64:67], v[194:197]
	s_and_b64 s[52:53], s[88:89], exec
	s_cselect_b32 s50, s69, s51
	s_lshl_b32 s52, s50, 15
	s_add_i32 s50, s29, s52
	v_add_u32_e32 v0, s50, v123
	v_add_u32_e32 v1, s50, v124
	ds_read_b128 v[218:221], v0
	ds_read_b128 v[222:225], v1
	v_add_u32_e32 v0, s50, v125
	v_add_u32_e32 v1, s50, v126
	ds_read_b128 v[226:229], v0
	ds_read_b128 v[230:233], v1
	s_waitcnt lgkmcnt(7)
	v_mfma_f32_16x16x32_bf16 v[198:201], v[240:243], v[52:55], 0
	s_waitcnt lgkmcnt(6)
	v_mfma_f32_16x16x32_bf16 v[198:201], v[244:247], v[56:59], v[198:201]
	s_waitcnt lgkmcnt(5)
	v_mfma_f32_16x16x32_bf16 v[198:201], v[248:251], v[60:63], v[198:201]
	s_waitcnt lgkmcnt(4)
	v_mfma_f32_16x16x32_bf16 v[198:201], v[252:255], v[64:67], v[198:201]
	s_and_b64 vcc, s[90:91], exec
	s_cselect_b32 s50, s69, s51
	s_lshl_b32 s53, s50, 15
	s_add_i32 s50, s30, s53
	v_add_u32_e32 v0, s50, v123
	v_add_u32_e32 v1, s50, v124
	ds_read_b128 v[240:243], v0
	ds_read_b128 v[244:247], v1
	v_add_u32_e32 v0, s50, v125
	v_add_u32_e32 v1, s50, v126
	ds_read_b128 v[248:251], v0
	ds_read_b128 v[252:255], v1
	s_waitcnt lgkmcnt(7)
	v_mfma_f32_16x16x32_bf16 v[202:205], v[218:221], v[52:55], 0
	s_waitcnt lgkmcnt(6)
	v_mfma_f32_16x16x32_bf16 v[202:205], v[222:225], v[56:59], v[202:205]
	s_waitcnt lgkmcnt(5)
	v_mfma_f32_16x16x32_bf16 v[202:205], v[226:229], v[60:63], v[202:205]
	s_waitcnt lgkmcnt(4)
	v_mfma_f32_16x16x32_bf16 v[202:205], v[230:233], v[64:67], v[202:205]
	s_and_b64 vcc, s[92:93], exec
	s_cselect_b32 s50, s69, s51
	s_lshl_b32 s50, s50, 15
	s_add_i32 s70, s31, s50
	v_add_u32_e32 v0, s70, v123
	v_add_u32_e32 v1, s70, v124
	ds_read_b128 v[218:221], v0
	ds_read_b128 v[222:225], v1
	v_add_u32_e32 v0, s70, v125
	v_add_u32_e32 v1, s70, v126
	ds_read_b128 v[226:229], v0
	ds_read_b128 v[230:233], v1
	s_waitcnt lgkmcnt(7)
	v_mfma_f32_16x16x32_bf16 v[206:209], v[240:243], v[52:55], 0
	s_waitcnt lgkmcnt(6)
	v_mfma_f32_16x16x32_bf16 v[206:209], v[244:247], v[56:59], v[206:209]
	s_waitcnt lgkmcnt(5)
	v_mfma_f32_16x16x32_bf16 v[206:209], v[248:251], v[60:63], v[206:209]
	s_waitcnt lgkmcnt(4)
	v_mfma_f32_16x16x32_bf16 v[206:209], v[252:255], v[64:67], v[206:209]
	s_and_b64 vcc, s[94:95], exec
	s_cselect_b32 s51, s69, s51
	s_lshl_b32 s51, s51, 15
	s_add_i32 s69, s38, s51
	v_add_u32_e32 v0, s69, v123
	v_add_u32_e32 v1, s69, v124
	ds_read_b128 v[240:243], v0
	ds_read_b128 v[244:247], v1
	v_add_u32_e32 v0, s69, v125
	v_add_u32_e32 v1, s69, v126
	ds_read_b128 v[248:251], v0
	ds_read_b128 v[252:255], v1
	s_waitcnt lgkmcnt(7)
	v_mfma_f32_16x16x32_bf16 v[210:213], v[218:221], v[52:55], 0
	s_waitcnt lgkmcnt(6)
	v_mfma_f32_16x16x32_bf16 v[210:213], v[222:225], v[56:59], v[210:213]
	s_waitcnt lgkmcnt(5)
	v_mfma_f32_16x16x32_bf16 v[210:213], v[226:229], v[60:63], v[210:213]
	s_waitcnt lgkmcnt(4)
	v_mfma_f32_16x16x32_bf16 v[210:213], v[230:233], v[64:67], v[210:213]
	s_add_i32 s39, s39, s40
	v_add_u32_e32 v0, s39, v123
	v_add_u32_e32 v1, s39, v124
	ds_read_b128 v[218:221], v0
	ds_read_b128 v[222:225], v1
	v_add_u32_e32 v0, s39, v125
	v_add_u32_e32 v1, s39, v126
	ds_read_b128 v[226:229], v0
	ds_read_b128 v[230:233], v1
	s_waitcnt lgkmcnt(7)
; #define LAS __attribute__((address_space(3)))
; __device__ __forceinline__ void segment(LAS unsigned char* lds, const bf16* __restrict__ QKV, bf16* __restrict__ Og, float* __restrict__ L2, int bl, int g, int h, int r, int dil, int n0, int cnt, int tid) {
;     ...
;         { bf16x8 kf[2][4];
;             { const int slot0 = (w >> 3) ? cur : prv; const LAS unsigned char* kb0 = lds + slot0 * SLOTB + (w & 7) * 4096;
; #pragma unroll
;               for (int s = 0; s < 4; ++s) kf[0][s] = *(const LAS bf16x8*)(kb0 + koff[s]); }
; #pragma unroll
;             for (int kt = 0; kt < 9; ++kt) {
;                 if (kt < 8) { const int tt = w + kt + 1; const int slot = (tt >> 3) ? cur : prv; const LAS unsigned char* kb = lds + slot * SLOTB + (tt & 7) * 4096;
; #pragma unroll
;                     for (int s = 0; s < 4; ++s) kf[(kt + 1) & 1][s] = *(const LAS bf16x8*)(kb + koff[s]); }
;                 f32x4 a = {0.f, 0.f, 0.f, 0.f};
; #pragma unroll
;                 for (int s = 0; s < 4; ++s) a = __builtin_amdgcn_mfma_f32_16x16x32_bf16(kf[kt & 1][s], qf[s], a, 0, 0, 0);
;                 sc[kt] = a;
;                 __builtin_amdgcn_sched_barrier(0); } }
;         const bool firstblk = (n == 0);
;         float mx = -INFINITY;
; #pragma unroll
;         for (int kt = 0; kt < 9; ++kt)
; #pragma unroll
;             for (int i = 0; i < 4; ++i) { float v = sc[kt][i] + (basel + cb * (float)(16 * kt + i)); bool valid = true;
;                 if (kt == 0) valid = (4 * gq + i >= lq);
;                 if (kt == 8) valid = (4 * gq + i <= lq);
;                 if (firstblk && (w + kt) < 8) valid = false;
;                 v = valid ? v : -INFINITY; sc[kt][i] = v; mx = fmaxf(mx, v); }
;         mx = fmaxf(mx, __shfl_xor(mx, 16)); mx = fmaxf(mx, __shfl_xor(mx, 32));
	v_mfma_f32_16x16x32_bf16 v[214:217], v[240:243], v[52:55], 0
	s_waitcnt lgkmcnt(6)
	v_mfma_f32_16x16x32_bf16 v[214:217], v[244:247], v[56:59], v[214:217]
	s_waitcnt lgkmcnt(5)
	v_mfma_f32_16x16x32_bf16 v[214:217], v[248:251], v[60:63], v[214:217]
	s_waitcnt lgkmcnt(4)
	v_mfma_f32_16x16x32_bf16 v[214:217], v[252:255], v[64:67], v[214:217]
	s_waitcnt lgkmcnt(3)
	v_mfma_f32_16x16x32_bf16 v[52:55], v[218:221], v[52:55], 0
	s_waitcnt lgkmcnt(2)
	v_mfma_f32_16x16x32_bf16 v[52:55], v[222:225], v[56:59], v[52:55]
	s_waitcnt lgkmcnt(1)
	v_mfma_f32_16x16x32_bf16 v[52:55], v[226:229], v[60:63], v[52:55]
	s_waitcnt lgkmcnt(0)
	v_mfma_f32_16x16x32_bf16 v[52:55], v[230:233], v[64:67], v[52:55]
	s_cmp_lg_u32 s37, 1
	s_cselect_b64 s[70:71], -1, 0
	s_or_b64 s[74:75], s[70:71], s[58:59]
	v_add_f32_e32 v0, v143, v186
	s_and_b64 vcc, s[74:75], s[4:5]
	v_cndmask_b32_e32 v0, v142, v0, vcc
	v_add_f32_e32 v1, v144, v187
	s_and_b64 vcc, s[74:75], s[6:7]
	v_cndmask_b32_e32 v1, v142, v1, vcc
	v_add_f32_e32 v56, v145, v188
	s_and_b64 vcc, s[74:75], s[8:9]
	v_cndmask_b32_e32 v56, v142, v56, vcc
	v_add_f32_e32 v57, v146, v189
	s_and_b64 vcc, s[74:75], s[10:11]
	v_cndmask_b32_e32 v57, v142, v57, vcc
	v_add_f32_e32 v58, v147, v190
	s_or_b64 vcc, s[70:71], s[0:1]
	v_cndmask_b32_e32 v60, v142, v58, vcc
	v_add_f32_e32 v58, v148, v191
	v_cndmask_b32_e32 v61, v142, v58, vcc
	v_add_f32_e32 v58, v149, v192
	v_cndmask_b32_e32 v62, v142, v58, vcc
	v_add_f32_e32 v58, v150, v193
	v_cndmask_b32_e32 v63, v142, v58, vcc
	v_add_f32_e32 v58, v151, v194
	s_or_b64 vcc, s[70:71], s[60:61]
	v_cndmask_b32_e32 v64, v142, v58, vcc
	v_add_f32_e32 v58, v152, v195
	v_cndmask_b32_e32 v65, v142, v58, vcc
	v_add_f32_e32 v58, v156, v196
	v_cndmask_b32_e32 v66, v142, v58, vcc
	v_add_f32_e32 v58, v157, v197
	v_cndmask_b32_e32 v67, v142, v58, vcc
	v_add_f32_e32 v58, v158, v198
	s_or_b64 vcc, s[70:71], s[62:63]
	v_cndmask_b32_e32 v118, v142, v58, vcc
	v_add_f32_e32 v58, v159, v199
	v_cndmask_b32_e32 v120, v142, v58, vcc
	v_add_f32_e32 v58, v160, v200
	v_cndmask_b32_e32 v121, v142, v58, vcc
	v_add_f32_e32 v58, v161, v201
	v_cndmask_b32_e32 v186, v142, v58, vcc
	v_add_f32_e32 v58, v162, v202
	s_or_b64 vcc, s[70:71], s[34:35]
	s_mov_b32 s39, 0xff800000
	v_cndmask_b32_e32 v187, v142, v58, vcc
	v_add_f32_e32 v58, v163, v203
	v_max3_f32 v2, v0, s39, v1
	v_cndmask_b32_e32 v188, v142, v58, vcc
	v_add_f32_e32 v58, v164, v204
	v_max3_f32 v2, v2, v56, v57
	v_cndmask_b32_e32 v189, v142, v58, vcc
	v_add_f32_e32 v58, v165, v205
	v_max3_f32 v2, v2, v60, v61
	v_cndmask_b32_e32 v190, v142, v58, vcc
	v_add_f32_e32 v58, v166, v206
	s_or_b64 vcc, s[70:71], s[64:65]
	v_max3_f32 v2, v2, v62, v63
	v_cndmask_b32_e32 v191, v142, v58, vcc
	v_add_f32_e32 v58, v167, v207
	v_max3_f32 v2, v2, v64, v65
	v_cndmask_b32_e32 v192, v142, v58, vcc
	v_add_f32_e32 v58, v168, v208
	v_max3_f32 v2, v2, v66, v67
	v_cndmask_b32_e32 v193, v142, v58, vcc
	v_add_f32_e32 v58, v169, v209
	v_max3_f32 v2, v2, v118, v120
	v_cndmask_b32_e32 v194, v142, v58, vcc
	v_add_f32_e32 v58, v170, v210
	s_or_b64 vcc, s[70:71], s[96:97]
	v_max3_f32 v2, v2, v121, v186
	v_cndmask_b32_e32 v195, v142, v58, vcc
	v_add_f32_e32 v58, v171, v211
	v_max3_f32 v2, v2, v187, v188
	v_cndmask_b32_e32 v196, v142, v58, vcc
	v_add_f32_e32 v58, v172, v212
	v_max3_f32 v2, v2, v189, v190
	v_cndmask_b32_e32 v197, v142, v58, vcc
	v_add_f32_e32 v58, v173, v213
	v_max3_f32 v2, v2, v191, v192
	v_cndmask_b32_e32 v198, v142, v58, vcc
	v_add_f32_e32 v58, v174, v214
	s_or_b64 vcc, s[70:71], s[20:21]
	v_max3_f32 v2, v2, v193, v194
	v_cndmask_b32_e32 v199, v142, v58, vcc
	v_add_f32_e32 v58, v175, v215
	v_max3_f32 v2, v2, v195, v196
	v_cndmask_b32_e32 v200, v142, v58, vcc
	v_add_f32_e32 v58, v176, v216
	v_add_f32_e32 v52, v178, v52
	v_max3_f32 v2, v2, v197, v198
	v_cndmask_b32_e32 v201, v142, v58, vcc
	v_add_f32_e32 v58, v177, v217
	v_cndmask_b32_e64 v203, v52, v142, s[12:13]
	v_add_f32_e32 v52, v179, v53
	v_max3_f32 v2, v2, v199, v200
	v_cndmask_b32_e32 v202, v142, v58, vcc
	v_cndmask_b32_e64 v204, v142, v52, s[14:15]
	v_add_f32_e32 v52, v180, v54
	v_max3_f32 v2, v2, v201, v202
	v_cndmask_b32_e64 v205, v52, v142, s[16:17]
	v_add_f32_e32 v52, v181, v55
	v_max3_f32 v2, v2, v203, v204
	v_cndmask_b32_e64 v206, v52, v142, s[18:19]
	v_max3_f32 v2, v2, v205, v206
	ds_bpermute_b32 v52, v139, v2
	s_add_i32 vcc_hi, s25, s72
	s_add_i32 s39, s68, s73
	s_add_i32 s69, s44, s36
	s_add_i32 s49, s48, s49
	s_waitcnt lgkmcnt(0)
	v_max_f32_e32 v52, v52, v52
	v_max_f32_e32 v2, v2, v52
	ds_bpermute_b32 v52, v140, v2
	s_add_i32 s36, s45, s52
	s_add_i32 s73, s67, s51
	s_add_i32 vcc_lo, s46, s53
	s_add_i32 s72, s66, s50
	s_waitcnt lgkmcnt(0)
; __device__ __forceinline__ unsigned cvtpk(float lo, float hi) { return pg8::cvt_pk_bf16(lo, hi); }
; #define ATT_LOADV(buf, cc, k0_, k1_) do { _Pragma("unroll") for (int ks_ = (k0_); ks_ < (k1_); ++ks_) { const int t0_ = w + 2 * ks_, t1_ = t0_ + 1; \
;             vf[buf][2 * ks_] = trd(lds + VBASE + ((t0_ >> 3) ? cur : prv) * SLOTB + (t0_ & 7) * 4096 + voff[cc]); \
;             vf[buf][2 * ks_ + 1] = trd(lds + VBASE + ((t1_ >> 3) ? cur : prv) * SLOTB + (t1_ & 7) * 4096 + voff[cc]); } } while (0)
; __device__ __forceinline__ void segment(LAS unsigned char* lds, const bf16* __restrict__ QKV, bf16* __restrict__ Og, float* __restrict__ L2, int bl, int g, int h, int r, int dil, int n0, int cnt, int tid) {
;     ...
;         mx = fmaxf(mx, __shfl_xor(mx, 16)); mx = fmaxf(mx, __shfl_xor(mx, 32));
;         float den = 0.f; unsigned pk[9][2];
; #pragma unroll
;         for (int kt = 0; kt < 9; ++kt) { const float p0 = __builtin_amdgcn_exp2f(sc[kt][0] - mx), p1 = __builtin_amdgcn_exp2f(sc[kt][1] - mx), p2 = __builtin_amdgcn_exp2f(sc[kt][2] - mx), p3 = __builtin_amdgcn_exp2f(sc[kt][3] - mx);
;             den += (p0 + p1) + (p2 + p3); pk[kt][0] = cvtpk(p0, p1); pk[kt][1] = cvtpk(p2, p3); }
;         den += __shfl_xor(den, 16); den += __shfl_xor(den, 32);
;         const float rden = __builtin_amdgcn_rcpf(den);
;         const size_t orow = rowbase + (size_t)(128 * n + 16 * w + lq) * dil;
;         bf16* op16 = Og + ((size_t)g * MH + orow) * 1024 + h * 128 + ((gq & 2) ? 16 + 8 * (gq - 2) : 8 * gq); v2u wprev = {0u, 0u};
;         s16x4 vf[2][9];
;     ...
;         ATT_LOADV(0, 0, 0, 2); ATT_LOADV(0, 0, 2, 4); ATT_LOADV8(0, 0);
; #pragma unroll
;         for (int c = 0; c < 8; ++c) { f32x4 a = {0.f, 0.f, 0.f, 0.f};
;             if (c < 7) ATT_LOADV((c + 1) & 1, c + 1, 0, 2);
;             ATT_PVMMA(0); ATT_PVMMA(1);
;             __builtin_amdgcn_sched_barrier(0);
;             if (c < 7) { ATT_LOADV((c + 1) & 1, c + 1, 2, 4); ATT_LOADV8((c + 1) & 1, c + 1); }
;             ATT_PVMMA(2); ATT_PVMMA(3);
;             { const s16x4 v8 = vf[c & 1][8];
;               const bf16x8 A8 = {v8[0], v8[1], v8[2], v8[3], 0, 0, 0, 0}; const v4u bw8 = {pk[8][0], pk[8][1], 0u, 0u};
;               a = __builtin_amdgcn_mfma_f32_16x16x32_bf16(A8, __builtin_bit_cast(bf16x8, bw8), a, 0, 0, 0); }
	v_max_f32_e32 v52, v52, v52
	v_max_f32_e32 v185, v2, v52
	v_sub_f32_e32 v1, v1, v185
	v_sub_f32_e32 v0, v0, v185
	v_exp_f32_e32 v52, v1
	v_sub_f32_e32 v1, v56, v185
	v_sub_f32_e32 v2, v57, v185
	v_exp_f32_e32 v0, v0
	v_exp_f32_e32 v1, v1
	v_exp_f32_e32 v53, v2
	v_sub_f32_e32 v2, v60, v185
	s_add_i32 s55, s25, s55
	v_add_u32_e32 v212, s69, v129
	v_pk_add_f32 v[54:55], v[0:1], v[52:53]
	v_cvt_pk_bf16_f32 v52, v0, v52
	v_pk_add_f32 v[58:59], v[54:55], v[54:55] op_sel_hi:[0,1]
	v_exp_f32_e32 v54, v2
	v_sub_f32_e32 v2, v61, v185
	v_exp_f32_e32 v55, v2
	v_sub_f32_e32 v2, v62, v185
	v_exp_f32_e32 v60, v2
	v_sub_f32_e32 v2, v63, v185
	v_exp_f32_e32 v61, v2
	v_sub_f32_e32 v2, v65, v185
	v_exp_f32_e32 v56, v2
	v_sub_f32_e32 v2, v66, v185
	v_sub_f32_e32 v0, v64, v185
	v_exp_f32_e32 v58, v2
	v_sub_f32_e32 v2, v67, v185
	v_exp_f32_e32 v0, v0
	v_exp_f32_e32 v2, v2
	v_cvt_pk_bf16_f32 v53, v1, v53
	v_add_f32_e32 v1, v54, v55
	v_add_f32_e32 v57, v60, v61
	v_cvt_pk_bf16_f32 v54, v54, v55
	v_cvt_pk_bf16_f32 v55, v60, v61
	v_pk_add_f32 v[60:61], v[0:1], v[56:57]
	v_pk_add_f32 v[62:63], v[58:59], v[2:3]
	v_sub_f32_e32 v1, v118, v185
	v_pk_add_f32 v[60:61], v[60:61], v[62:63]
	v_exp_f32_e32 v62, v1
	v_sub_f32_e32 v1, v120, v185
	v_exp_f32_e32 v64, v1
	v_sub_f32_e32 v1, v121, v185
	v_exp_f32_e32 v63, v1
	v_sub_f32_e32 v1, v186, v185
	v_exp_f32_e32 v65, v1
	v_cvt_pk_bf16_f32 v56, v0, v56
	v_cvt_pk_bf16_f32 v57, v58, v2
	v_sub_f32_e32 v2, v188, v185
	v_pk_add_f32 v[0:1], v[62:63], v[64:65]
	v_sub_f32_e32 v58, v189, v185
	v_pk_add_f32 v[0:1], v[0:1], v[0:1] op_sel_hi:[0,1]
	v_sub_f32_e32 v0, v187, v185
	v_pk_add_f32 v[66:67], v[60:61], v[60:61] op_sel_hi:[0,1]
	v_exp_f32_e32 v0, v0
	v_exp_f32_e32 v2, v2
	v_exp_f32_e32 v61, v58
	v_sub_f32_e32 v58, v190, v185
	v_exp_f32_e32 v66, v58
	v_cvt_pk_bf16_f32 v59, v63, v65
	v_add_f32_e32 v63, v0, v2
	v_cvt_pk_bf16_f32 v60, v0, v2
	v_sub_f32_e32 v0, v191, v185
	v_sub_f32_e32 v2, v194, v185
	v_cvt_pk_bf16_f32 v58, v62, v64
	v_add_f32_e32 v65, v61, v66
	v_cvt_pk_bf16_f32 v61, v61, v66
	v_exp_f32_e32 v62, v0
	v_sub_f32_e32 v0, v192, v185
	v_exp_f32_e32 v66, v2
	v_sub_f32_e32 v2, v195, v185
	v_exp_f32_e32 v64, v0
	v_sub_f32_e32 v0, v193, v185
	v_exp_f32_e32 v186, v2
	v_sub_f32_e32 v2, v196, v185
	v_exp_f32_e32 v0, v0
	v_exp_f32_e32 v188, v2
	v_sub_f32_e32 v2, v197, v185
	v_exp_f32_e32 v187, v2
	v_sub_f32_e32 v2, v198, v185
	v_exp_f32_e32 v189, v2
	v_pk_add_f32 v[120:121], v[62:63], v[64:65]
	v_sub_f32_e32 v63, v201, v185
	v_pk_add_f32 v[190:191], v[0:1], v[66:67]
	v_exp_f32_e32 v67, v63
	v_sub_f32_e32 v63, v202, v185
	v_exp_f32_e32 v118, v63
	v_sub_f32_e32 v63, v203, v185
	v_pk_add_f32 v[120:121], v[120:121], v[190:191]
	v_pk_add_f32 v[190:191], v[186:187], v[188:189]
	v_exp_f32_e32 v192, v63
	v_sub_f32_e32 v63, v204, v185
	v_pk_add_f32 v[190:191], v[190:191], v[190:191] op_sel_hi:[0,1]
	v_sub_f32_e32 v1, v199, v185
	v_sub_f32_e32 v2, v200, v185
	v_exp_f32_e32 v194, v63
	v_sub_f32_e32 v63, v205, v185
	v_pk_add_f32 v[120:121], v[120:121], v[120:121] op_sel_hi:[0,1]
	v_exp_f32_e32 v1, v1
	v_exp_f32_e32 v2, v2
	v_exp_f32_e32 v190, v63
	v_sub_f32_e32 v63, v206, v185
	v_exp_f32_e32 v120, v63
	v_add_f32_e32 v193, v1, v2
	v_add_f32_e32 v195, v67, v118
	v_pk_add_f32 v[196:197], v[192:193], v[194:195]
	v_pk_add_f32 v[198:199], v[190:191], v[120:121]
	v_cvt_pk_bf16_f32 v62, v62, v64
	v_pk_add_f32 v[196:197], v[196:197], v[198:199]
	v_cvt_pk_bf16_f32 v64, v186, v188
	v_add_f32_e32 v121, v196, v197
	ds_bpermute_b32 v191, v139, v121
	v_cvt_pk_bf16_f32 v63, v0, v66
	v_cvt_pk_bf16_f32 v66, v1, v2
	v_add_u32_e32 v2, vcc_hi, v128
	v_cvt_pk_bf16_f32 v65, v187, v189
	s_waitcnt lgkmcnt(0)
	v_add_f32_e32 v121, v121, v191
	ds_bpermute_b32 v186, v140, v121
	v_cvt_pk_bf16_f32 v67, v67, v118
	v_cvt_pk_bf16_f32 v0, v192, v194
	v_cvt_pk_bf16_f32 v1, v190, v120
	v_add_u32_e32 v118, s39, v128
	s_waitcnt lgkmcnt(0)
	v_add_f32_e32 v186, v121, v186
	v_add_u32_e32 v120, s69, v128
	v_add_u32_e32 v121, s49, v128
	ds_read_b64_tr_b16 v[188:189], v2
	ds_read_b64_tr_b16 v[190:191], v118
	ds_read_b64_tr_b16 v[192:193], v120
	ds_read_b64_tr_b16 v[194:195], v121
	v_add_u32_e32 v2, s36, v128
	v_add_u32_e32 v187, s73, v128
	v_add_u32_e32 v120, vcc_lo, v128
	v_add_u32_e32 v121, s72, v128
	ds_read_b64_tr_b16 v[196:197], v2
	ds_read_b64_tr_b16 v[198:199], v120
	ds_read_b64_tr_b16 v[200:201], v121
	ds_read_b64_tr_b16 v[202:203], v187
	v_add_u32_e32 v187, s55, v128
	v_add_u32_e32 v206, vcc_hi, v129
	v_add_u32_e32 v207, s39, v129
	ds_read_b64_tr_b16 v[204:205], v187
	ds_read_b64_tr_b16 v[208:209], v206
	ds_read_b64_tr_b16 v[210:211], v207
	ds_read_b64_tr_b16 v[212:213], v212
	v_add_u32_e32 v187, s49, v129
	s_waitcnt lgkmcnt(10)
	v_mfma_f32_16x16x32_bf16 v[188:191], v[188:191], v[52:55], 0
	ds_read_b64_tr_b16 v[214:215], v187
	v_rcp_f32_e32 v118, v186
	v_lshl_add_u64 v[120:121], v[104:105], 0, s[56:57]
	v_mov_b32_e32 v2, v3
	s_waitcnt lgkmcnt(9)
	v_mfma_f32_16x16x32_bf16 v[188:191], v[192:195], v[56:59], v[188:191]
	s_waitcnt lgkmcnt(7)
	v_mfma_f32_16x16x32_bf16 v[188:191], v[196:199], v[60:63], v[188:191]
	v_mov_b32_e32 v206, v3
	v_mov_b32_e32 v207, v3
	v_add_u32_e32 v187, s36, v129
	s_waitcnt lgkmcnt(5)
	v_mfma_f32_16x16x32_bf16 v[188:191], v[200:203], v[64:67], v[188:191]
	v_add_u32_e32 v194, vcc_lo, v129
	v_add_u32_e32 v196, s72, v129
	v_add_u32_e32 v198, s73, v129
	ds_read_b64_tr_b16 v[192:193], v187
	ds_read_b64_tr_b16 v[194:195], v194
	ds_read_b64_tr_b16 v[196:197], v196
	ds_read_b64_tr_b16 v[198:199], v198
	v_add_u32_e32 v187, s55, v129
	s_waitcnt lgkmcnt(8)
; __device__ __forceinline__ unsigned cvtpk(float lo, float hi) { return pg8::cvt_pk_bf16(lo, hi); }
; #define ATT_LOADV(buf, cc, k0_, k1_) do { _Pragma("unroll") for (int ks_ = (k0_); ks_ < (k1_); ++ks_) { const int t0_ = w + 2 * ks_, t1_ = t0_ + 1; \
;             vf[buf][2 * ks_] = trd(lds + VBASE + ((t0_ >> 3) ? cur : prv) * SLOTB + (t0_ & 7) * 4096 + voff[cc]); \
;             vf[buf][2 * ks_ + 1] = trd(lds + VBASE + ((t1_ >> 3) ? cur : prv) * SLOTB + (t1_ & 7) * 4096 + voff[cc]); } } while (0)
; #define ATT_LOADV8(buf, cc) do { const int t8_ = w + 8; vf[buf][8] = trd(lds + VBASE + cur * SLOTB + (t8_ & 7) * 4096 + voff[cc]); } while (0)
; __device__ __forceinline__ void segment(LAS unsigned char* lds, const bf16* __restrict__ QKV, bf16* __restrict__ Og, float* __restrict__ L2, int bl, int g, int h, int r, int dil, int n0, int cnt, int tid) {
;     ...
;         ATT_LOADV(0, 0, 0, 2); ATT_LOADV(0, 0, 2, 4); ATT_LOADV8(0, 0);
; #pragma unroll
;         for (int c = 0; c < 8; ++c) { f32x4 a = {0.f, 0.f, 0.f, 0.f};
;             if (c < 7) ATT_LOADV((c + 1) & 1, c + 1, 0, 2);
;             ATT_PVMMA(0); ATT_PVMMA(1);
;             __builtin_amdgcn_sched_barrier(0);
;             if (c < 7) { ATT_LOADV((c + 1) & 1, c + 1, 2, 4); ATT_LOADV8((c + 1) & 1, c + 1); }
;             ATT_PVMMA(2); ATT_PVMMA(3);
;             { const s16x4 v8 = vf[c & 1][8];
;               const bf16x8 A8 = {v8[0], v8[1], v8[2], v8[3], 0, 0, 0, 0}; const v4u bw8 = {pk[8][0], pk[8][1], 0u, 0u};
;               a = __builtin_amdgcn_mfma_f32_16x16x32_bf16(A8, __builtin_bit_cast(bf16x8, bw8), a, 0, 0, 0); }
;             v2u wv; wv.x = cvtpk(a[0] * rden, a[1] * rden); wv.y = cvtpk(a[2] * rden, a[3] * rden);
;             if (c & 1) {
;                 const auto rx = __builtin_amdgcn_permlane32_swap(wprev.x, wv.x, false, false); const auto ry = __builtin_amdgcn_permlane32_swap(wprev.y, wv.y, false, false);
;                 v4u o4; o4.x = rx[0]; o4.y = ry[0]; o4.z = rx[1]; o4.w = ry[1];
;                 *(v4u*)(op16 + 32 * (c >> 1)) = o4; }
;             else wprev = wv;
;             __builtin_amdgcn_sched_barrier(0); }
	v_mfma_f32_16x16x32_bf16 v[188:191], v[204:207], v[0:3], v[188:191]
	ds_read_b64_tr_b16 v[200:201], v187
	s_nop 6
	v_pk_mul_f32 v[190:191], v[118:119], v[190:191] op_sel_hi:[0,1]
	v_pk_mul_f32 v[188:189], v[118:119], v[188:189] op_sel_hi:[0,1]
	v_cvt_pk_bf16_f32 v191, v190, v191
	v_cvt_pk_bf16_f32 v190, v188, v189
	v_add_u32_e32 v187, vcc_hi, v130
	v_add_u32_e32 v218, s49, v130
	v_add_u32_e32 v188, s39, v130
	v_add_u32_e32 v189, s69, v130
	s_waitcnt lgkmcnt(7)
	v_mfma_f32_16x16x32_bf16 v[202:205], v[208:211], v[52:55], 0
	ds_read_b64_tr_b16 v[206:207], v187
	ds_read_b64_tr_b16 v[208:209], v188
	ds_read_b64_tr_b16 v[216:217], v189
	ds_read_b64_tr_b16 v[218:219], v218
	s_waitcnt lgkmcnt(9)
	v_mfma_f32_16x16x32_bf16 v[202:205], v[212:215], v[56:59], v[202:205]
	s_waitcnt lgkmcnt(7)
	v_mfma_f32_16x16x32_bf16 v[192:195], v[192:195], v[60:63], v[202:205]
	v_add_u32_e32 v187, s36, v130
	v_add_u32_e32 v188, vcc_lo, v130
	v_add_u32_e32 v189, s72, v130
	s_nop 2
	v_mov_b32_e32 v202, v3
	v_mov_b32_e32 v203, v3
	s_waitcnt lgkmcnt(5)
	v_mfma_f32_16x16x32_bf16 v[192:195], v[196:199], v[64:67], v[192:195]
	v_add_u32_e32 v204, s73, v130
	ds_read_b64_tr_b16 v[196:197], v187
	ds_read_b64_tr_b16 v[198:199], v188
	ds_read_b64_tr_b16 v[210:211], v189
	ds_read_b64_tr_b16 v[212:213], v204
	v_add_u32_e32 v187, s55, v130
	s_waitcnt lgkmcnt(8)
	v_mfma_f32_16x16x32_bf16 v[200:203], v[200:203], v[0:3], v[192:195]
	ds_read_b64_tr_b16 v[188:189], v187
	s_nop 6
	v_pk_mul_f32 v[192:193], v[118:119], v[202:203] op_sel_hi:[0,1]
	v_pk_mul_f32 v[194:195], v[118:119], v[200:201] op_sel_hi:[0,1]
	v_cvt_pk_bf16_f32 v193, v192, v193
	v_cvt_pk_bf16_f32 v192, v194, v195
	s_nop 1
	v_permlane32_swap_b32_e32 v190, v192
	v_permlane32_swap_b32_e32 v191, v193
	global_store_dwordx4 v[120:121], v[190:193], off
	v_add_u32_e32 v187, vcc_hi, v131
	v_add_u32_e32 v194, s39, v131
	v_add_u32_e32 v195, s69, v131
	v_add_u32_e32 v214, s49, v131
	s_waitcnt lgkmcnt(7)
	v_mfma_f32_16x16x32_bf16 v[190:193], v[206:209], v[52:55], 0
	ds_read_b64_tr_b16 v[200:201], v187
	ds_read_b64_tr_b16 v[202:203], v194
	ds_read_b64_tr_b16 v[204:205], v195
	ds_read_b64_tr_b16 v[206:207], v214
	s_waitcnt lgkmcnt(9)
	v_mfma_f32_16x16x32_bf16 v[190:193], v[216:219], v[56:59], v[190:193]
	s_waitcnt lgkmcnt(7)
	v_mfma_f32_16x16x32_bf16 v[192:195], v[196:199], v[60:63], v[190:193]
	v_add_u32_e32 v187, s36, v131
	v_add_u32_e32 v208, vcc_lo, v131
	v_add_u32_e32 v209, s72, v131
	s_nop 2
	v_mov_b32_e32 v190, v3
	v_mov_b32_e32 v191, v3
	s_waitcnt lgkmcnt(5)
	v_mfma_f32_16x16x32_bf16 v[192:195], v[210:213], v[64:67], v[192:195]
	v_add_u32_e32 v214, s73, v131
	ds_read_b64_tr_b16 v[196:197], v187
	ds_read_b64_tr_b16 v[198:199], v208
	ds_read_b64_tr_b16 v[208:209], v209
	ds_read_b64_tr_b16 v[210:211], v214
	v_add_u32_e32 v187, s55, v131
	s_waitcnt lgkmcnt(8)
	v_mfma_f32_16x16x32_bf16 v[188:191], v[188:191], v[0:3], v[192:195]
	ds_read_b64_tr_b16 v[212:213], v187
	s_nop 6
	v_pk_mul_f32 v[190:191], v[118:119], v[190:191] op_sel_hi:[0,1]
	v_pk_mul_f32 v[188:189], v[118:119], v[188:189] op_sel_hi:[0,1]
	v_cvt_pk_bf16_f32 v191, v190, v191
	v_cvt_pk_bf16_f32 v190, v188, v189
	v_add_u32_e32 v187, vcc_hi, v132
	v_add_u32_e32 v188, s39, v132
	v_add_u32_e32 v189, s69, v132
	v_add_u32_e32 v214, s49, v132
	s_waitcnt lgkmcnt(7)
	v_mfma_f32_16x16x32_bf16 v[192:195], v[200:203], v[52:55], 0
	ds_read_b64_tr_b16 v[200:201], v187
	ds_read_b64_tr_b16 v[202:203], v188
	ds_read_b64_tr_b16 v[216:217], v189
	ds_read_b64_tr_b16 v[218:219], v214
	s_waitcnt lgkmcnt(9)
	v_mfma_f32_16x16x32_bf16 v[192:195], v[204:207], v[56:59], v[192:195]
	s_waitcnt lgkmcnt(7)
	v_mfma_f32_16x16x32_bf16 v[192:195], v[196:199], v[60:63], v[192:195]
	v_mov_b32_e32 v214, v3
	v_mov_b32_e32 v215, v3
	v_add_u32_e32 v187, s36, v132
	s_waitcnt lgkmcnt(5)
	v_mfma_f32_16x16x32_bf16 v[192:195], v[208:211], v[64:67], v[192:195]
	v_add_u32_e32 v206, s73, v132
	v_add_u32_e32 v188, vcc_lo, v132
	v_add_u32_e32 v189, s72, v132
	ds_read_b64_tr_b16 v[196:197], v187
	ds_read_b64_tr_b16 v[198:199], v188
	ds_read_b64_tr_b16 v[204:205], v189
	ds_read_b64_tr_b16 v[206:207], v206
	s_waitcnt lgkmcnt(8)
	v_mfma_f32_16x16x32_bf16 v[208:211], v[212:215], v[0:3], v[192:195]
	v_add_u32_e32 v187, s55, v132
	ds_read_b64_tr_b16 v[188:189], v187
	s_nop 5
	v_pk_mul_f32 v[192:193], v[118:119], v[210:211] op_sel_hi:[0,1]
	v_pk_mul_f32 v[194:195], v[118:119], v[208:209] op_sel_hi:[0,1]
	v_cvt_pk_bf16_f32 v193, v192, v193
	v_cvt_pk_bf16_f32 v192, v194, v195
	s_nop 1
	v_permlane32_swap_b32_e32 v190, v192
	v_permlane32_swap_b32_e32 v191, v193
	global_store_dwordx4 v[120:121], v[190:193], off offset:64
	v_add_u32_e32 v187, vcc_hi, v133
	v_add_u32_e32 v210, s49, v133
	v_add_u32_e32 v194, s39, v133
	v_add_u32_e32 v195, s69, v133
	s_waitcnt lgkmcnt(7)
; __device__ __forceinline__ unsigned cvtpk(float lo, float hi) { return pg8::cvt_pk_bf16(lo, hi); }
; #define ATT_LOADV(buf, cc, k0_, k1_) do { _Pragma("unroll") for (int ks_ = (k0_); ks_ < (k1_); ++ks_) { const int t0_ = w + 2 * ks_, t1_ = t0_ + 1; \
;             vf[buf][2 * ks_] = trd(lds + VBASE + ((t0_ >> 3) ? cur : prv) * SLOTB + (t0_ & 7) * 4096 + voff[cc]); \
;             vf[buf][2 * ks_ + 1] = trd(lds + VBASE + ((t1_ >> 3) ? cur : prv) * SLOTB + (t1_ & 7) * 4096 + voff[cc]); } } while (0)
; #define ATT_LOADV8(buf, cc) do { const int t8_ = w + 8; vf[buf][8] = trd(lds + VBASE + cur * SLOTB + (t8_ & 7) * 4096 + voff[cc]); } while (0)
; __device__ __forceinline__ void segment(LAS unsigned char* lds, const bf16* __restrict__ QKV, bf16* __restrict__ Og, float* __restrict__ L2, int bl, int g, int h, int r, int dil, int n0, int cnt, int tid) {
;     ...
;         ATT_LOADV(0, 0, 0, 2); ATT_LOADV(0, 0, 2, 4); ATT_LOADV8(0, 0);
; #pragma unroll
;         for (int c = 0; c < 8; ++c) { f32x4 a = {0.f, 0.f, 0.f, 0.f};
;             if (c < 7) ATT_LOADV((c + 1) & 1, c + 1, 0, 2);
;             ATT_PVMMA(0); ATT_PVMMA(1);
;             __builtin_amdgcn_sched_barrier(0);
;             if (c < 7) { ATT_LOADV((c + 1) & 1, c + 1, 2, 4); ATT_LOADV8((c + 1) & 1, c + 1); }
;             ATT_PVMMA(2); ATT_PVMMA(3);
;             { const s16x4 v8 = vf[c & 1][8];
;               const bf16x8 A8 = {v8[0], v8[1], v8[2], v8[3], 0, 0, 0, 0}; const v4u bw8 = {pk[8][0], pk[8][1], 0u, 0u};
;               a = __builtin_amdgcn_mfma_f32_16x16x32_bf16(A8, __builtin_bit_cast(bf16x8, bw8), a, 0, 0, 0); }
;             v2u wv; wv.x = cvtpk(a[0] * rden, a[1] * rden); wv.y = cvtpk(a[2] * rden, a[3] * rden);
;             if (c & 1) {
;                 const auto rx = __builtin_amdgcn_permlane32_swap(wprev.x, wv.x, false, false); const auto ry = __builtin_amdgcn_permlane32_swap(wprev.y, wv.y, false, false);
;                 v4u o4; o4.x = rx[0]; o4.y = ry[0]; o4.z = rx[1]; o4.w = ry[1];
;                 *(v4u*)(op16 + 32 * (c >> 1)) = o4; }
;             else wprev = wv;
;             __builtin_amdgcn_sched_barrier(0); }
;     ...
;         if (gq == 0) L2[((size_t)g * MH + orow) * 8 + h] = mx + __builtin_amdgcn_logf(den);
;         __syncthreads();
	v_mfma_f32_16x16x32_bf16 v[190:193], v[200:203], v[52:55], 0
	ds_read_b64_tr_b16 v[200:201], v187
	ds_read_b64_tr_b16 v[202:203], v194
	ds_read_b64_tr_b16 v[208:209], v195
	ds_read_b64_tr_b16 v[210:211], v210
	s_waitcnt lgkmcnt(9)
	v_mfma_f32_16x16x32_bf16 v[190:193], v[216:219], v[56:59], v[190:193]
	s_waitcnt lgkmcnt(7)
	v_mfma_f32_16x16x32_bf16 v[192:195], v[196:199], v[60:63], v[190:193]
	v_add_u32_e32 v187, s36, v133
	v_add_u32_e32 v212, vcc_lo, v133
	v_add_u32_e32 v213, s72, v133
	s_nop 2
	v_mov_b32_e32 v190, v3
	v_mov_b32_e32 v191, v3
	s_waitcnt lgkmcnt(5)
	v_mfma_f32_16x16x32_bf16 v[192:195], v[204:207], v[64:67], v[192:195]
	v_add_u32_e32 v214, s73, v133
	ds_read_b64_tr_b16 v[196:197], v187
	ds_read_b64_tr_b16 v[198:199], v212
	ds_read_b64_tr_b16 v[204:205], v213
	ds_read_b64_tr_b16 v[206:207], v214
	v_add_u32_e32 v187, s55, v133
	s_waitcnt lgkmcnt(8)
	v_mfma_f32_16x16x32_bf16 v[188:191], v[188:191], v[0:3], v[192:195]
	ds_read_b64_tr_b16 v[212:213], v187
	s_nop 6
	v_pk_mul_f32 v[190:191], v[118:119], v[190:191] op_sel_hi:[0,1]
	v_pk_mul_f32 v[188:189], v[118:119], v[188:189] op_sel_hi:[0,1]
	v_cvt_pk_bf16_f32 v191, v190, v191
	v_cvt_pk_bf16_f32 v190, v188, v189
	v_add_u32_e32 v187, vcc_hi, v134
	v_add_u32_e32 v188, s39, v134
	v_add_u32_e32 v189, s69, v134
	v_add_u32_e32 v214, s49, v134
	s_waitcnt lgkmcnt(7)
	v_mfma_f32_16x16x32_bf16 v[192:195], v[200:203], v[52:55], 0
	ds_read_b64_tr_b16 v[200:201], v187
	ds_read_b64_tr_b16 v[202:203], v188
	ds_read_b64_tr_b16 v[216:217], v189
	ds_read_b64_tr_b16 v[218:219], v214
	s_waitcnt lgkmcnt(9)
	v_mfma_f32_16x16x32_bf16 v[192:195], v[208:211], v[56:59], v[192:195]
	s_waitcnt lgkmcnt(7)
	v_mfma_f32_16x16x32_bf16 v[192:195], v[196:199], v[60:63], v[192:195]
	v_mov_b32_e32 v214, v3
	v_add_u32_e32 v187, s36, v134
	v_add_u32_e32 v208, s73, v134
	s_waitcnt lgkmcnt(5)
	v_mfma_f32_16x16x32_bf16 v[192:195], v[204:207], v[64:67], v[192:195]
	v_add_u32_e32 v188, vcc_lo, v134
	v_add_u32_e32 v189, s72, v134
	ds_read_b64_tr_b16 v[196:197], v187
	ds_read_b64_tr_b16 v[198:199], v188
	ds_read_b64_tr_b16 v[204:205], v189
	ds_read_b64_tr_b16 v[206:207], v208
	s_waitcnt lgkmcnt(8)
	v_mfma_f32_16x16x32_bf16 v[208:211], v[212:215], v[0:3], v[192:195]
	v_add_u32_e32 v187, s55, v134
	ds_read_b64_tr_b16 v[188:189], v187
	s_nop 5
	v_pk_mul_f32 v[192:193], v[118:119], v[210:211] op_sel_hi:[0,1]
	v_pk_mul_f32 v[194:195], v[118:119], v[208:209] op_sel_hi:[0,1]
	v_cvt_pk_bf16_f32 v193, v192, v193
	v_cvt_pk_bf16_f32 v192, v194, v195
	s_nop 1
	v_permlane32_swap_b32_e32 v190, v192
	v_permlane32_swap_b32_e32 v191, v193
	global_store_dwordx4 v[120:121], v[190:193], off offset:128
	v_add_u32_e32 v187, vcc_hi, v135
	v_add_u32_e32 v210, s49, v135
	v_add_u32_e32 v194, s39, v135
	v_add_u32_e32 v195, s69, v135
	s_waitcnt lgkmcnt(7)
	v_mfma_f32_16x16x32_bf16 v[190:193], v[200:203], v[52:55], 0
	ds_read_b64_tr_b16 v[200:201], v187
	ds_read_b64_tr_b16 v[202:203], v194
	ds_read_b64_tr_b16 v[208:209], v195
	ds_read_b64_tr_b16 v[210:211], v210
	s_waitcnt lgkmcnt(9)
	v_mfma_f32_16x16x32_bf16 v[190:193], v[216:219], v[56:59], v[190:193]
	s_waitcnt lgkmcnt(7)
	v_mfma_f32_16x16x32_bf16 v[192:195], v[196:199], v[60:63], v[190:193]
	v_add_u32_e32 v187, s36, v135
	v_add_u32_e32 v212, vcc_lo, v135
	v_add_u32_e32 v213, s72, v135
	s_nop 2
	v_mov_b32_e32 v190, v3
	v_mov_b32_e32 v191, v3
	s_waitcnt lgkmcnt(5)
	v_mfma_f32_16x16x32_bf16 v[192:195], v[204:207], v[64:67], v[192:195]
	v_add_u32_e32 v214, s73, v135
	ds_read_b64_tr_b16 v[196:197], v187
	ds_read_b64_tr_b16 v[198:199], v212
	ds_read_b64_tr_b16 v[204:205], v213
	ds_read_b64_tr_b16 v[206:207], v214
	v_add_u32_e32 v187, s55, v135
	s_waitcnt lgkmcnt(8)
	v_mfma_f32_16x16x32_bf16 v[188:191], v[188:191], v[0:3], v[192:195]
	ds_read_b64_tr_b16 v[212:213], v187
	s_nop 6
	v_pk_mul_f32 v[190:191], v[118:119], v[190:191] op_sel_hi:[0,1]
	v_pk_mul_f32 v[188:189], v[118:119], v[188:189] op_sel_hi:[0,1]
	v_cvt_pk_bf16_f32 v191, v190, v191
	v_cvt_pk_bf16_f32 v190, v188, v189
	s_waitcnt lgkmcnt(7)
	v_mfma_f32_16x16x32_bf16 v[52:55], v[200:203], v[52:55], 0
	s_waitcnt lgkmcnt(5)
	v_mfma_f32_16x16x32_bf16 v[52:55], v[208:211], v[56:59], v[52:55]
	s_waitcnt lgkmcnt(3)
	v_mfma_f32_16x16x32_bf16 v[52:55], v[196:199], v[60:63], v[52:55]
	v_mov_b32_e32 v214, v3
	s_waitcnt lgkmcnt(1)
	v_mfma_f32_16x16x32_bf16 v[52:55], v[204:207], v[64:67], v[52:55]
	s_waitcnt lgkmcnt(0)
	v_mfma_f32_16x16x32_bf16 v[52:55], v[212:215], v[0:3], v[52:55]
	s_nop 7
	v_pk_mul_f32 v[0:1], v[118:119], v[54:55] op_sel_hi:[0,1]
	v_pk_mul_f32 v[52:53], v[118:119], v[52:53] op_sel_hi:[0,1]
	v_cvt_pk_bf16_f32 v193, v0, v1
	v_cvt_pk_bf16_f32 v192, v52, v53
	s_nop 1
	v_permlane32_swap_b32_e32 v190, v192
	v_permlane32_swap_b32_e32 v191, v193
	global_store_dwordx4 v[120:121], v[190:193], off offset:192
	s_and_saveexec_b64 vcc, s[2:3]
	s_cbranch_execz .LBB0_449
	v_log_f32_e32 v0, v186
	s_nop 0
	v_add_f32_e32 v0, v185, v0
	global_store_dword v[102:103], v0, off
	s_branch .LBB0_449

; __global__ void __launch_bounds__(NTHREADS, 2) trunk_fwd(Args args) {
	.amdhsa_kernel _Z9trunk_fwd4Args
		.amdhsa_group_segment_fixed_size 0
		.amdhsa_private_segment_fixed_size 0
		.amdhsa_kernarg_size 376
		.amdhsa_user_sgpr_count 2
		.amdhsa_user_sgpr_dispatch_ptr 0
		.amdhsa_user_sgpr_queue_ptr 0
		.amdhsa_user_sgpr_kernarg_segment_ptr 1
		.amdhsa_user_sgpr_dispatch_id 0
		.amdhsa_user_sgpr_kernarg_preload_length 0
		.amdhsa_user_sgpr_kernarg_preload_offset 0
		.amdhsa_user_sgpr_private_segment_size 0
		.amdhsa_uses_dynamic_stack 0
		.amdhsa_enable_private_segment 0
		.amdhsa_system_sgpr_workgroup_id_x 1
		.amdhsa_system_sgpr_workgroup_id_y 0
		.amdhsa_system_sgpr_workgroup_id_z 0
		.amdhsa_system_sgpr_workgroup_info 0
		.amdhsa_system_vgpr_workitem_id 2
		.amdhsa_next_free_vgpr 256
		.amdhsa_next_free_sgpr 100
		.amdhsa_accum_offset 256
		.amdhsa_reserve_vcc 1
		.amdhsa_float_round_mode_32 0
		.amdhsa_float_round_mode_16_64 0
		.amdhsa_float_denorm_mode_32 3
		.amdhsa_float_denorm_mode_16_64 3
		.amdhsa_dx10_clamp 1
		.amdhsa_ieee_mode 1
		.amdhsa_fp16_overflow 0
		.amdhsa_tg_split 0
		.amdhsa_exception_fp_ieee_invalid_op 0
		.amdhsa_exception_fp_denorm_src 0
		.amdhsa_exception_fp_ieee_div_zero 0
		.amdhsa_exception_fp_ieee_overflow 0
		.amdhsa_exception_fp_ieee_underflow 0
		.amdhsa_exception_fp_ieee_inexact 0
		.amdhsa_exception_int_div_zero 0
	.end_amdhsa_kernel

; __global__ void __launch_bounds__(NTHREADS, 2) trunk_fwd(Args args) {
amdhsa.kernels:
  - .agpr_count:     0
    .args:
      - .offset:         0
        .size:           120
        .value_kind:     by_value
      - .offset:         120
        .size:           4
        .value_kind:     hidden_block_count_x
      - .offset:         124
        .size:           4
        .value_kind:     hidden_block_count_y
      - .offset:         128
        .size:           4
        .value_kind:     hidden_block_count_z
      - .offset:         132
        .size:           2
        .value_kind:     hidden_group_size_x
      - .offset:         134
        .size:           2
        .value_kind:     hidden_group_size_y
      - .offset:         136
        .size:           2
        .value_kind:     hidden_group_size_z
      - .offset:         138
        .size:           2
        .value_kind:     hidden_remainder_x
      - .offset:         140
        .size:           2
        .value_kind:     hidden_remainder_y
      - .offset:         142
        .size:           2
        .value_kind:     hidden_remainder_z
      - .offset:         160
        .size:           8
        .value_kind:     hidden_global_offset_x
      - .offset:         168
        .size:           8
        .value_kind:     hidden_global_offset_y
      - .offset:         176
        .size:           8
        .value_kind:     hidden_global_offset_z
      - .offset:         184
        .size:           2
        .value_kind:     hidden_grid_dims
      - .offset:         208
        .size:           8
        .value_kind:     hidden_multigrid_sync_arg
      - .offset:         240
        .size:           4
        .value_kind:     hidden_dynamic_lds_size
    .group_segment_fixed_size: 0
    .kernarg_segment_align: 8
    .kernarg_segment_size: 376
    .language:       OpenCL C
    .language_version:
      - 2
      - 0
    .max_flat_workgroup_size: 512
    .name:           _Z9trunk_fwd4Args
    .private_segment_fixed_size: 0
    .sgpr_count:     106
    .sgpr_spill_count: 107
    .symbol:         _Z9trunk_fwd4Args.kd
    .uniform_work_group_size: 1
    .uses_dynamic_stack: false
    .vgpr_count:     256
    .vgpr_spill_count: 0
    .wavefront_size: 64
